# attention loops: also drop hipcc's post-inline-asm s_nop pads after v_max3 (no hazard: plain VALU->VALU); on top of negm-copy removal and G1 norm-gain load hoist
# speedup vs baseline: 1.0165x; 1.0024x over previous
; #define LAS __attribute__((address_space(3)))
; template <int DV, int PAR, bool KW = true, bool KL = true, bool VL = true>
; __device__ __forceinline__ void attn_iter_full(AttnState<DV>& S, int t, LAS unsigned char* lds) {
;     ...
;     sn0 = S.negm; sn1 = S.negm;
;     u32x4 pw[4]; float mxa = 0.f, mxb = 0.f, mx = 0.f; f32x16 ssum;
;     constexpr int PD = (DV == 64) ? 3 : 2; bf16x8 fr[PD + 1];
;     ...
; #pragma unroll
;     for (int i = 0; i < PD; ++i) fr[i] = AT_FRAG(i);
;     __builtin_amdgcn_sched_barrier(0);
; #pragma unroll
;     for (int i = 0; i < NS; ++i) {
;         if (i + PD < NS) fr[(i + PD) % (PD + 1)] = AT_FRAG(i + PD);
;         if (i == 3) {
;             if (KW) *(LAS u32x4*)(lds + AT_K0 + PAR * AT_KB + S.kl) = S.kreg;
;             LAS unsigned char* W = lds + AT_V0 + (PAR ^ 1) * AT_VB + S.vl; *(LAS u32x4*)W = S.vreg0; if (DV == 128) *(LAS u32x4*)(W + 64 * 144) = S.vreg1; }
;         if (i == 5) { if (KL) S.kreg = *(const u32x4*)(S.kg + (size_t)(t + 3) * 4096);
;             if (VL) { S.vreg0 = *(const u32x4*)(S.vg + (t + 2) * 64); if (DV == 128) S.vreg1 = *(const u32x4*)(S.vg + (size_t)64 * TK + (t + 2) * 64); } }
;         if (i < 8) { if (i & 1) sn1 = MFMA32(fr[i % (PD + 1)], S.qr[i >> 1], sn1); else sn0 = MFMA32(fr[i % (PD + 1)], S.qr[i >> 1], sn0); }
;         else { const int j = i - 8; S.o[j % NDB] = MFMA32(fr[i % (PD + 1)], __builtin_bit_cast(bf16x8, pw[j / NDB]), S.o[j % NDB]); }
; #pragma unroll
;         for (int u = 0; u < NU; ++u) {
;             if (u * NS / NU != i) continue;
;             if (u < 20) {
;                 const int q = u / 5, r = u % 5;
;                 if (r < 4) { const int e = 8 * q + 2 * r;
;                     if (e < 16) { C0[e] = fast_exp2(C0[e]); C0[e + 1] = fast_exp2(C0[e + 1]); }
;                     else { C1[e - 16] = fast_exp2(C1[e - 16]); C1[e - 15] = fast_exp2(C1[e - 15]); } }
;                 else { if (q < 2) { const int b0 = 8 * q; pw[q].x = pk2(C0[b0], C0[b0 + 1]); pw[q].y = pk2(C0[b0 + 2], C0[b0 + 3]); pw[q].z = pk2(C0[b0 + 4], C0[b0 + 5]); pw[q].w = pk2(C0[b0 + 6], C0[b0 + 7]); }
;                        else { const int b0 = 8 * (q - 2); pw[q].x = pk2(C1[b0], C1[b0 + 1]); pw[q].y = pk2(C1[b0 + 2], C1[b0 + 3]); pw[q].z = pk2(C1[b0 + 4], C1[b0 + 5]); pw[q].w = pk2(C1[b0 + 6], C1[b0 + 7]); } }
;             } else if (u == 20) { ssum = C0 + C1; }
.LBB0_397:
	ds_read_b128 v[32:35], v169 offset:9216
	ds_read_b128 v[36:39], v169 offset:13824
	ds_read_b128 v[40:43], v169 offset:9248
	s_waitcnt lgkmcnt(2)
	v_mfma_f32_32x32x16_bf16 v[112:127], v[32:35], v[140:143], v[64:79]
	ds_read_b128 v[44:47], v169 offset:13856
	v_exp_f32_e32 v32, v82
	v_exp_f32_e32 v34, v80
	v_exp_f32_e32 v35, v81
	v_exp_f32_e32 v33, v83
	s_waitcnt lgkmcnt(2)
	v_mfma_f32_32x32x16_bf16 v[96:111], v[36:39], v[140:143], v[64:79]
	ds_read_b128 v[80:83], v169 offset:9280
	v_exp_f32_e32 v38, v84
	v_exp_f32_e32 v39, v85
	v_exp_f32_e32 v36, v86
	v_exp_f32_e32 v37, v87
	s_waitcnt lgkmcnt(2)
	v_mfma_f32_32x32x16_bf16 v[112:127], v[40:43], v[136:139], v[112:127]
	ds_read_b128 v[84:87], v169 offset:13888
	v_lshl_add_u64 v[162:163], v[156:157], 0, v[160:161]
	v_lshl_add_u64 v[164:165], v[158:159], 0, v[160:161]
	v_cvt_pk_bf16_f32 v40, v34, v35
	v_cvt_pk_bf16_f32 v41, v32, v33
	v_cvt_pk_bf16_f32 v42, v38, v39
	v_cvt_pk_bf16_f32 v43, v36, v37
	v_exp_f32_e32 v176, v88
	v_exp_f32_e32 v177, v89
	s_waitcnt lgkmcnt(2)
	v_mfma_f32_32x32x16_bf16 v[96:111], v[44:47], v[136:139], v[96:111]
	ds_read_b128 v[172:175], v169 offset:9312
	s_waitcnt vmcnt(1)
	ds_write_b128 v168, v[144:147]
	s_waitcnt vmcnt(0)
	ds_write_b128 v168, v[148:151] offset:36864
	v_exp_f32_e32 v178, v90
	v_exp_f32_e32 v179, v91
	s_waitcnt lgkmcnt(4)
	v_mfma_f32_32x32x16_bf16 v[112:127], v[80:83], v[132:135], v[112:127]
	ds_read_b128 v[44:47], v169 offset:13920
	v_exp_f32_e32 v92, v92
	v_exp_f32_e32 v93, v93
	v_exp_f32_e32 v94, v94
	v_exp_f32_e32 v95, v95
	s_mov_b32 s4, 0x16306000
	v_add_co_u32_e32 v88, vcc, s4, v162
	s_mov_b32 s4, 0x16c00000
	s_nop 0
	v_addc_co_u32_e32 v89, vcc, 0, v163, vcc
	v_add_co_u32_e32 v164, vcc, s4, v164
	ds_read_b128 v[80:83], v167 offset:18432
	s_nop 0
	v_addc_co_u32_e32 v165, vcc, 0, v165, vcc
	global_load_dwordx4 v[144:147], v[88:89], off
	global_load_dwordx4 v[148:151], v[164:165], off offset:256
	s_waitcnt lgkmcnt(5)
	v_mfma_f32_32x32x16_bf16 v[96:111], v[84:87], v[132:135], v[96:111]
	v_cvt_pk_bf16_f32 v84, v176, v177
	v_exp_f32_e32 v180, v48
	v_exp_f32_e32 v181, v49
	v_cvt_pk_bf16_f32 v85, v178, v179
	v_cvt_pk_bf16_f32 v86, v92, v93
	v_cvt_pk_bf16_f32 v87, v94, v95
	s_waitcnt lgkmcnt(4)
	v_mfma_f32_32x32x16_bf16 v[112:127], v[172:175], v[128:131], v[112:127]
	ds_read_b128 v[88:91], v167 offset:23040
	v_exp_f32_e32 v172, v50
	v_exp_f32_e32 v173, v51
	s_waitcnt lgkmcnt(2)
	v_mfma_f32_32x32x16_bf16 v[96:111], v[44:47], v[128:131], v[96:111]
	ds_read_b128 v[48:51], v167 offset:18464
	v_exp_f32_e32 v174, v52
	v_exp_f32_e32 v175, v53
	v_exp_f32_e32 v182, v54
	v_exp_f32_e32 v183, v55
	s_waitcnt lgkmcnt(2)
	v_mfma_f32_32x32x16_bf16 v[0:15], v[80:83], v[40:43], v[0:15]
	ds_read_b128 v[44:47], v167 offset:23072
	v_cvt_pk_bf16_f32 v52, v180, v181
	v_cvt_pk_bf16_f32 v53, v172, v173
	v_cvt_pk_bf16_f32 v54, v174, v175
	v_cvt_pk_bf16_f32 v55, v182, v183
	v_exp_f32_e32 v56, v56
	v_exp_f32_e32 v57, v57
	s_waitcnt lgkmcnt(2)
	v_mfma_f32_32x32x16_bf16 v[16:31], v[88:91], v[40:43], v[16:31]
	ds_read_b128 v[80:83], v167 offset:18496
	v_exp_f32_e32 v58, v58
	v_exp_f32_e32 v59, v59
	s_waitcnt lgkmcnt(2)
	v_mfma_f32_32x32x16_bf16 v[0:15], v[48:51], v[84:87], v[0:15]
	ds_read_b128 v[40:43], v167 offset:23104
	v_exp_f32_e32 v60, v60
	v_exp_f32_e32 v61, v61
	v_exp_f32_e32 v62, v62
	v_exp_f32_e32 v63, v63
	s_waitcnt lgkmcnt(2)
	v_mfma_f32_32x32x16_bf16 v[16:31], v[44:47], v[84:87], v[16:31]
	ds_read_b128 v[48:51], v167 offset:18528
	v_cvt_pk_bf16_f32 v44, v56, v57
	v_cvt_pk_bf16_f32 v45, v58, v59
	v_cvt_pk_bf16_f32 v46, v60, v61
	v_cvt_pk_bf16_f32 v47, v62, v63
	v_pk_add_f32 v[60:61], v[60:61], v[92:93]
	v_pk_add_f32 v[62:63], v[62:63], v[94:95]
	v_pk_add_f32 v[58:59], v[58:59], v[178:179]
	v_pk_add_f32 v[56:57], v[56:57], v[176:177]
	v_pk_add_f32 v[38:39], v[174:175], v[38:39]
	v_pk_add_f32 v[84:85], v[180:181], v[34:35]
	v_pk_add_f32 v[36:37], v[182:183], v[36:37]
	v_pk_add_f32 v[86:87], v[172:173], v[32:33]
	s_waitcnt lgkmcnt(2)
	v_mfma_f32_32x32x16_bf16 v[0:15], v[80:83], v[52:55], v[0:15]
	v_add_f32_e64 v36, v86, v36
	v_add_f32_e64 v37, v87, v37
	v_add_f32_e64 v38, v84, v38
	v_add_f32_e64 v39, v85, v39
	v_add_f32_e64 v36, v58, v36
	v_add_f32_e64 v37, v59, v37
	v_pk_add_f32 v[38:39], v[56:57], v[38:39]
	ds_read_b128 v[32:35], v167 offset:23136
	v_pk_add_f32 v[36:37], v[62:63], v[36:37]
	v_pk_add_f32 v[38:39], v[60:61], v[38:39]
	s_nop 0
	v_pk_mov_b32 v[56:57], v[38:39], v[36:37] op_sel:[1,0]
	v_mov_b32_e32 v39, v37
	v_pk_add_f32 v[36:37], v[56:57], v[38:39]
	s_nop 0
	v_add_f32_e32 v36, v36, v37
	v_add_f32_e32 v171, v171, v36
	s_waitcnt lgkmcnt(2)
	v_mfma_f32_32x32x16_bf16 v[16:31], v[40:43], v[52:55], v[16:31]
	v_max3_f32 v36, v112, v113, v96
	v_max3_f32 v37, v114, v115, v97
	v_max3_f32 v36, v36, v98, v99
	v_max3_f32 v37, v37, v118, v119
	v_max3_f32 v36, v36, v116, v117
	v_max3_f32 v37, v37, v102, v103
	v_max3_f32 v36, v36, v100, v101
	s_waitcnt lgkmcnt(1)
	v_mfma_f32_32x32x16_bf16 v[0:15], v[48:51], v[44:47], v[0:15]
	v_max3_f32 v36, v36, v120, v121
	v_max3_f32 v37, v37, v122, v123
	v_max3_f32 v36, v36, v104, v105
	v_max3_f32 v37, v37, v106, v107
	v_max3_f32 v36, v36, v124, v125
	v_max3_f32 v37, v37, v126, v127
	v_max3_f32 v36, v36, v108, v109
	v_max3_f32 v37, v37, v110, v111
	s_waitcnt lgkmcnt(0)
	v_mfma_f32_32x32x16_bf16 v[16:31], v[32:35], v[44:47], v[16:31]
	v_max_f32_e32 v32, v36, v37
	v_mov_b32_e32 v33, v32
	s_nop 1
	v_permlane32_swap_b32_e32 v32, v33
	v_max_f32_e32 v32, v32, v33
	s_nop 0
	v_cmp_lt_f32_e32 vcc, s3, v32
	s_cbranch_vccz .LBB0_399
; #define LAS __attribute__((address_space(3)))
; __device__ __forceinline__ float fast_exp2(float x) { return __builtin_amdgcn_exp2f(x); }
; #define MFMA32(a, b, c) __builtin_amdgcn_mfma_f32_32x32x16_bf16((a), (b), (c), 0, 0, 0)
; #define AT_FRAG(i) (((i) < 8) ? lds_rd16v(BK + ((i) & 1) * 32 * 144 + ((i) >> 1) * 32) \
;                               : lds_rd16v(BV + (((i) - 8) % NDB) * 32 * 144 + (32 * ((((i) - 8) / NDB) >> 1) + 16 * ((((i) - 8) / NDB) & 1)) * 2))
; template <int DV, int PAR, bool KW = true, bool KL = true, bool VL = true>
; __device__ __forceinline__ void attn_iter_full(AttnState<DV>& S, int t, LAS unsigned char* lds) {
;     ...
;     sn0 = S.negm; sn1 = S.negm;
;     u32x4 pw[4]; float mxa = 0.f, mxb = 0.f, mx = 0.f; f32x16 ssum;
;     constexpr int PD = (DV == 64) ? 3 : 2; bf16x8 fr[PD + 1];
;     ...
; #pragma unroll
;     for (int i = 0; i < PD; ++i) fr[i] = AT_FRAG(i);
;     __builtin_amdgcn_sched_barrier(0);
; #pragma unroll
;     for (int i = 0; i < NS; ++i) {
;         if (i + PD < NS) fr[(i + PD) % (PD + 1)] = AT_FRAG(i + PD);
;         if (i == 3) {
;             if (KW) *(LAS u32x4*)(lds + AT_K0 + PAR * AT_KB + S.kl) = S.kreg;
;             LAS unsigned char* W = lds + AT_V0 + (PAR ^ 1) * AT_VB + S.vl; *(LAS u32x4*)W = S.vreg0; if (DV == 128) *(LAS u32x4*)(W + 64 * 144) = S.vreg1; }
;         if (i == 5) { if (KL) S.kreg = *(const u32x4*)(S.kg + (size_t)(t + 3) * 4096);
;             if (VL) { S.vreg0 = *(const u32x4*)(S.vg + (t + 2) * 64); if (DV == 128) S.vreg1 = *(const u32x4*)(S.vg + (size_t)64 * TK + (t + 2) * 64); } }
;         if (i < 8) { if (i & 1) sn1 = MFMA32(fr[i % (PD + 1)], S.qr[i >> 1], sn1); else sn0 = MFMA32(fr[i % (PD + 1)], S.qr[i >> 1], sn0); }
;         else { const int j = i - 8; S.o[j % NDB] = MFMA32(fr[i % (PD + 1)], __builtin_bit_cast(bf16x8, pw[j / NDB]), S.o[j % NDB]); }
;     ...
;     if (__any(mx > 8.0f)) {
;         const float dl = fmaxf(mx, 0.f), alpha = fast_exp2(-dl);
;         S.mrun += dl; S.lsum *= alpha;
; #pragma unroll
;         for (int i = 0; i < 16; ++i) { sn0[i] -= dl; sn1[i] -= dl; S.negm[i] = -S.mrun; }
; #pragma unroll
;         for (int d = 0; d < NDB; ++d)
; #pragma unroll
;             for (int i = 0; i < 16; ++i) S.o[d][i] *= alpha;
;     }
	v_max_f32_e32 v32, v32, v32
	v_max_f32_e32 v34, 0, v32
	v_exp_f32_e64 v36, -v34
	v_add_f32_e32 v170, v170, v34
	v_xor_b32_e32 v32, 0x80000000, v170
	v_pk_add_f32 v[112:113], v[112:113], v[34:35] op_sel_hi:[1,0] neg_lo:[0,1] neg_hi:[0,1]
	v_mul_f32_e32 v171, v171, v36
	v_pk_add_f32 v[96:97], v[96:97], v[34:35] op_sel_hi:[1,0] neg_lo:[0,1] neg_hi:[0,1]
	v_pk_add_f32 v[114:115], v[114:115], v[34:35] op_sel_hi:[1,0] neg_lo:[0,1] neg_hi:[0,1]
	v_pk_add_f32 v[98:99], v[98:99], v[34:35] op_sel_hi:[1,0] neg_lo:[0,1] neg_hi:[0,1]
	v_pk_add_f32 v[116:117], v[116:117], v[34:35] op_sel_hi:[1,0] neg_lo:[0,1] neg_hi:[0,1]
	v_pk_add_f32 v[100:101], v[100:101], v[34:35] op_sel_hi:[1,0] neg_lo:[0,1] neg_hi:[0,1]
	v_pk_add_f32 v[118:119], v[118:119], v[34:35] op_sel_hi:[1,0] neg_lo:[0,1] neg_hi:[0,1]
	v_pk_add_f32 v[102:103], v[102:103], v[34:35] op_sel_hi:[1,0] neg_lo:[0,1] neg_hi:[0,1]
	v_pk_add_f32 v[120:121], v[120:121], v[34:35] op_sel_hi:[1,0] neg_lo:[0,1] neg_hi:[0,1]
	v_pk_add_f32 v[104:105], v[104:105], v[34:35] op_sel_hi:[1,0] neg_lo:[0,1] neg_hi:[0,1]
	v_pk_add_f32 v[122:123], v[122:123], v[34:35] op_sel_hi:[1,0] neg_lo:[0,1] neg_hi:[0,1]
	v_pk_add_f32 v[106:107], v[106:107], v[34:35] op_sel_hi:[1,0] neg_lo:[0,1] neg_hi:[0,1]
	v_pk_add_f32 v[124:125], v[124:125], v[34:35] op_sel_hi:[1,0] neg_lo:[0,1] neg_hi:[0,1]
	v_pk_add_f32 v[108:109], v[108:109], v[34:35] op_sel_hi:[1,0] neg_lo:[0,1] neg_hi:[0,1]
	v_pk_add_f32 v[126:127], v[126:127], v[34:35] op_sel_hi:[1,0] neg_lo:[0,1] neg_hi:[0,1]
	v_pk_add_f32 v[110:111], v[110:111], v[34:35] op_sel_hi:[1,0] neg_lo:[0,1] neg_hi:[0,1]
	v_pk_mul_f32 v[14:15], v[14:15], v[36:37] op_sel_hi:[1,0]
	v_pk_mul_f32 v[12:13], v[12:13], v[36:37] op_sel_hi:[1,0]
	v_pk_mul_f32 v[10:11], v[10:11], v[36:37] op_sel_hi:[1,0]
	v_pk_mul_f32 v[8:9], v[8:9], v[36:37] op_sel_hi:[1,0]
	v_pk_mul_f32 v[6:7], v[6:7], v[36:37] op_sel_hi:[1,0]
	v_pk_mul_f32 v[4:5], v[4:5], v[36:37] op_sel_hi:[1,0]
	v_pk_mul_f32 v[2:3], v[2:3], v[36:37] op_sel_hi:[1,0]
	v_pk_mul_f32 v[0:1], v[0:1], v[36:37] op_sel_hi:[1,0]
	v_pk_mul_f32 v[30:31], v[30:31], v[36:37] op_sel_hi:[1,0]
	v_pk_mul_f32 v[28:29], v[28:29], v[36:37] op_sel_hi:[1,0]
	v_pk_mul_f32 v[26:27], v[26:27], v[36:37] op_sel_hi:[1,0]
	v_pk_mul_f32 v[24:25], v[24:25], v[36:37] op_sel_hi:[1,0]
	v_pk_mul_f32 v[22:23], v[22:23], v[36:37] op_sel_hi:[1,0]
	v_pk_mul_f32 v[20:21], v[20:21], v[36:37] op_sel_hi:[1,0]
	v_pk_mul_f32 v[18:19], v[18:19], v[36:37] op_sel_hi:[1,0]
	v_pk_mul_f32 v[16:17], v[16:17], v[36:37] op_sel_hi:[1,0]
	v_mov_b32_e32 v33, v32
	v_mov_b32_e32 v34, v32
	v_mov_b32_e32 v35, v32
	v_mov_b32_e32 v36, v32
	v_mov_b32_e32 v37, v32
	v_mov_b32_e32 v38, v32
	v_mov_b32_e32 v39, v32
	v_mov_b32_e32 v40, v32
	v_mov_b32_e32 v41, v32
	v_mov_b32_e32 v42, v32
	v_mov_b32_e32 v43, v32
	v_mov_b32_e32 v44, v32
	v_mov_b32_e32 v45, v32
	v_mov_b32_e32 v46, v32
	v_mov_b32_e32 v47, v32
	v_mov_b32_e32 v64, v32
	v_mov_b32_e32 v65, v32
	v_mov_b32_e32 v66, v32
	v_mov_b32_e32 v67, v32
	v_mov_b32_e32 v68, v32
	v_mov_b32_e32 v69, v32
	v_mov_b32_e32 v70, v32
	v_mov_b32_e32 v71, v32
	v_mov_b32_e32 v72, v32
	v_mov_b32_e32 v73, v32
	v_mov_b32_e32 v74, v32
	v_mov_b32_e32 v75, v32
	v_mov_b32_e32 v76, v32
	v_mov_b32_e32 v77, v32
	v_mov_b32_e32 v78, v32
	v_mov_b32_e32 v79, v32
	s_branch .LBB0_400
.LBB0_399:
.LBB0_400:
	s_barrier
	ds_read_b128 v[48:51], v169
	ds_read_b128 v[172:175], v169 offset:4608
	ds_read_b128 v[176:179], v169 offset:32
	s_waitcnt lgkmcnt(2)
	v_mfma_f32_32x32x16_bf16 v[80:95], v[48:51], v[140:143], v[64:79]
	ds_read_b128 v[180:183], v169 offset:4640
	v_exp_f32_e32 v184, v112
	v_exp_f32_e32 v185, v113
	v_exp_f32_e32 v186, v114
	v_exp_f32_e32 v187, v115
	s_waitcnt lgkmcnt(2)
	v_mfma_f32_32x32x16_bf16 v[48:63], v[172:175], v[140:143], v[64:79]
	ds_read_b128 v[112:115], v169 offset:64
	v_exp_f32_e32 v188, v116
	v_exp_f32_e32 v189, v117
	v_exp_f32_e32 v190, v118
	v_exp_f32_e32 v191, v119
	s_waitcnt lgkmcnt(2)
	v_mfma_f32_32x32x16_bf16 v[80:95], v[176:179], v[136:139], v[80:95]
	ds_read_b128 v[116:119], v169 offset:4672
	v_cvt_pk_bf16_f32 v172, v184, v185
	v_cvt_pk_bf16_f32 v173, v186, v187
	v_cvt_pk_bf16_f32 v174, v188, v189
	v_cvt_pk_bf16_f32 v175, v190, v191
	v_exp_f32_e32 v192, v120
	v_exp_f32_e32 v193, v121
	s_waitcnt lgkmcnt(2)
	v_mfma_f32_32x32x16_bf16 v[48:63], v[180:183], v[136:139], v[48:63]
	ds_read_b128 v[176:179], v169 offset:96
	s_waitcnt vmcnt(1)
	ds_write_b128 v168, v[144:147] offset:9216
	s_waitcnt vmcnt(0)
	ds_write_b128 v168, v[148:151] offset:18432
	v_exp_f32_e32 v196, v122
	v_exp_f32_e32 v197, v123
	s_waitcnt lgkmcnt(4)
	v_mfma_f32_32x32x16_bf16 v[80:95], v[112:115], v[132:135], v[80:95]
	ds_read_b128 v[120:123], v169 offset:4704
	v_exp_f32_e32 v180, v124
	v_exp_f32_e32 v181, v125
	v_exp_f32_e32 v182, v126
	v_exp_f32_e32 v183, v127
	s_mov_b32 s4, 0x16308000
	v_add_co_u32_e32 v124, vcc, s4, v162
	ds_read_b128 v[112:115], v167 offset:36864
	s_nop 0
	v_addc_co_u32_e32 v125, vcc, 0, v163, vcc
	global_load_dwordx4 v[144:147], v[124:125], off
	global_load_dwordx4 v[148:151], v[164:165], off offset:384
	s_waitcnt lgkmcnt(5)
	v_mfma_f32_32x32x16_bf16 v[48:63], v[116:119], v[132:135], v[48:63]
	v_cvt_pk_bf16_f32 v116, v192, v193
	v_exp_f32_e32 v162, v96
	v_exp_f32_e32 v163, v97
	v_cvt_pk_bf16_f32 v117, v196, v197
	v_cvt_pk_bf16_f32 v118, v180, v181
	v_cvt_pk_bf16_f32 v119, v182, v183
	s_waitcnt lgkmcnt(4)
	v_mfma_f32_32x32x16_bf16 v[80:95], v[176:179], v[128:131], v[80:95]
	ds_read_b128 v[124:127], v167 offset:41472
	v_exp_f32_e32 v164, v98
	v_exp_f32_e32 v165, v99
	s_waitcnt lgkmcnt(2)
; template <int DV, int PAR, bool KW = true, bool KL = true, bool VL = true>
; __device__ __forceinline__ void attn_iter_full(AttnState<DV>& S, int t, LAS unsigned char* lds) {
;     ...
;         if (i < 8) { if (i & 1) sn1 = MFMA32(fr[i % (PD + 1)], S.qr[i >> 1], sn1); else sn0 = MFMA32(fr[i % (PD + 1)], S.qr[i >> 1], sn0); }
;         else { const int j = i - 8; S.o[j % NDB] = MFMA32(fr[i % (PD + 1)], __builtin_bit_cast(bf16x8, pw[j / NDB]), S.o[j % NDB]); }
; #pragma unroll
;         for (int u = 0; u < NU; ++u) {
;             if (u * NS / NU != i) continue;
;             if (u < 20) {
;                 const int q = u / 5, r = u % 5;
;                 if (r < 4) { const int e = 8 * q + 2 * r;
;                     if (e < 16) { C0[e] = fast_exp2(C0[e]); C0[e + 1] = fast_exp2(C0[e + 1]); }
;                     else { C1[e - 16] = fast_exp2(C1[e - 16]); C1[e - 15] = fast_exp2(C1[e - 15]); } }
;                 else { if (q < 2) { const int b0 = 8 * q; pw[q].x = pk2(C0[b0], C0[b0 + 1]); pw[q].y = pk2(C0[b0 + 2], C0[b0 + 3]); pw[q].z = pk2(C0[b0 + 4], C0[b0 + 5]); pw[q].w = pk2(C0[b0 + 6], C0[b0 + 7]); }
;                        else { const int b0 = 8 * (q - 2); pw[q].x = pk2(C1[b0], C1[b0 + 1]); pw[q].y = pk2(C1[b0 + 2], C1[b0 + 3]); pw[q].z = pk2(C1[b0 + 4], C1[b0 + 5]); pw[q].w = pk2(C1[b0 + 6], C1[b0 + 7]); } }
;             } else if (u == 20) { ssum = C0 + C1; }
;             else if (u == 21) { const f32x4 a = (f32x4){ssum[0], ssum[1], ssum[2], ssum[3]} + (f32x4){ssum[4], ssum[5], ssum[6], ssum[7]} + (f32x4){ssum[8], ssum[9], ssum[10], ssum[11]} + (f32x4){ssum[12], ssum[13], ssum[14], ssum[15]};
;                 S.lsum += (a[0] + a[1]) + (a[2] + a[3]); }
;             else if (u == 22) { mxa = max3f(sn0[0], sn0[1], sn1[0]); mxb = max3f(sn0[2], sn0[3], sn1[1]); mxa = max3f(mxa, sn1[2], sn1[3]); }
;             else if (u < 26) { const int r = 4 * (u - 22); mxa = max3f(mxa, sn0[r], sn0[r + 1]); mxb = max3f(mxb, sn0[r + 2], sn0[r + 3]); mxa = max3f(mxa, sn1[r], sn1[r + 1]); mxb = max3f(mxb, sn1[r + 2], sn1[r + 3]); }
;             else { const float m = max2f(mxa, mxb); auto rr = __builtin_amdgcn_permlane32_swap(__float_as_uint(m), __float_as_uint(m), false, false); mx = max2f(__uint_as_float(rr[0]), __uint_as_float(rr[1])); }
;         }
;         __builtin_amdgcn_sched_barrier(0);
;     }
;     ...
;     if (__any(mx > 8.0f)) {
	v_mfma_f32_32x32x16_bf16 v[48:63], v[120:123], v[128:131], v[48:63]
	ds_read_b128 v[96:99], v167 offset:36896
	v_exp_f32_e32 v176, v100
	v_exp_f32_e32 v177, v101
	v_exp_f32_e32 v178, v102
	v_exp_f32_e32 v179, v103
	s_waitcnt lgkmcnt(2)
	v_mfma_f32_32x32x16_bf16 v[0:15], v[112:115], v[172:175], v[0:15]
	ds_read_b128 v[100:103], v167 offset:41504
	v_cvt_pk_bf16_f32 v112, v162, v163
	v_cvt_pk_bf16_f32 v113, v164, v165
	v_cvt_pk_bf16_f32 v114, v176, v177
	v_cvt_pk_bf16_f32 v115, v178, v179
	v_exp_f32_e32 v198, v104
	v_exp_f32_e32 v199, v105
	s_waitcnt lgkmcnt(2)
	v_mfma_f32_32x32x16_bf16 v[16:31], v[124:127], v[172:175], v[16:31]
	ds_read_b128 v[120:123], v167 offset:36928
	v_exp_f32_e32 v124, v106
	v_exp_f32_e32 v125, v107
	s_waitcnt lgkmcnt(2)
	v_mfma_f32_32x32x16_bf16 v[0:15], v[96:99], v[116:119], v[0:15]
	ds_read_b128 v[104:107], v167 offset:41536
	v_exp_f32_e32 v108, v108
	v_exp_f32_e32 v109, v109
	v_exp_f32_e32 v110, v110
	v_exp_f32_e32 v111, v111
	s_waitcnt lgkmcnt(2)
	v_mfma_f32_32x32x16_bf16 v[16:31], v[100:103], v[116:119], v[16:31]
	ds_read_b128 v[96:99], v167 offset:36960
	v_cvt_pk_bf16_f32 v100, v198, v199
	v_cvt_pk_bf16_f32 v101, v124, v125
	v_cvt_pk_bf16_f32 v102, v108, v109
	v_cvt_pk_bf16_f32 v103, v110, v111
	v_pk_add_f32 v[116:117], v[108:109], v[180:181]
	v_pk_add_f32 v[118:119], v[110:111], v[182:183]
	v_pk_add_f32 v[124:125], v[124:125], v[196:197]
	v_pk_add_f32 v[126:127], v[198:199], v[192:193]
	v_pk_add_f32 v[172:173], v[176:177], v[188:189]
	v_pk_add_f32 v[162:163], v[162:163], v[184:185]
	v_pk_add_f32 v[174:175], v[178:179], v[190:191]
	v_pk_add_f32 v[164:165], v[164:165], v[186:187]
	s_waitcnt lgkmcnt(2)
	v_mfma_f32_32x32x16_bf16 v[0:15], v[120:123], v[112:115], v[0:15]
	v_add_f32_e64 v120, v164, v174
	v_add_f32_e64 v121, v165, v175
	v_add_f32_e64 v122, v162, v172
	v_add_f32_e64 v123, v163, v173
	v_add_f32_e64 v120, v124, v120
	v_add_f32_e64 v121, v125, v121
	v_pk_add_f32 v[122:123], v[126:127], v[122:123]
	v_pk_add_f32 v[118:119], v[118:119], v[120:121]
	v_pk_add_f32 v[116:117], v[116:117], v[122:123]
	ds_read_b128 v[108:111], v167 offset:41568
	v_pk_mov_b32 v[120:121], v[116:117], v[118:119] op_sel:[1,0]
	v_mov_b32_e32 v117, v119
	v_pk_add_f32 v[116:117], v[120:121], v[116:117]
	s_nop 0
	v_add_f32_e32 v116, v116, v117
	v_add_f32_e32 v171, v171, v116
	s_waitcnt lgkmcnt(2)
	v_mfma_f32_32x32x16_bf16 v[16:31], v[104:107], v[112:115], v[16:31]
	v_max3_f32 v104, v80, v81, v48
	v_max3_f32 v105, v82, v83, v49
	v_max3_f32 v104, v104, v50, v51
	v_max3_f32 v105, v105, v86, v87
	v_max3_f32 v104, v104, v84, v85
	v_max3_f32 v105, v105, v54, v55
	v_max3_f32 v104, v104, v52, v53
	s_waitcnt lgkmcnt(1)
	v_mfma_f32_32x32x16_bf16 v[0:15], v[96:99], v[100:103], v[0:15]
	v_max3_f32 v96, v104, v88, v89
	v_max3_f32 v97, v105, v90, v91
	v_max3_f32 v96, v96, v56, v57
	v_max3_f32 v97, v97, v58, v59
	v_max3_f32 v96, v96, v92, v93
	v_max3_f32 v97, v97, v94, v95
	v_max3_f32 v96, v96, v60, v61
	v_max3_f32 v97, v97, v62, v63
	s_waitcnt lgkmcnt(0)
	v_mfma_f32_32x32x16_bf16 v[16:31], v[108:111], v[100:103], v[16:31]
	v_max_f32_e32 v96, v96, v97
	v_mov_b32_e32 v97, v96
	s_nop 1
	v_permlane32_swap_b32_e32 v96, v97
	v_max_f32_e32 v96, v96, v97
	s_nop 0
	v_cmp_lt_f32_e32 vcc, s3, v96
	s_cbranch_vccz .LBB0_396
	v_max_f32_e32 v32, v96, v96
	v_max_f32_e32 v33, 0, v32
	v_exp_f32_e64 v34, -v33
	v_add_f32_e32 v170, v170, v33
	v_xor_b32_e32 v32, 0x80000000, v170
	v_sub_f32_e32 v95, v95, v33
	v_mul_f32_e32 v171, v171, v34
	v_sub_f32_e32 v94, v94, v33
	v_sub_f32_e32 v93, v93, v33
	v_sub_f32_e32 v92, v92, v33
	v_sub_f32_e32 v91, v91, v33
	v_sub_f32_e32 v90, v90, v33
	v_sub_f32_e32 v89, v89, v33
	v_sub_f32_e32 v88, v88, v33
	v_sub_f32_e32 v87, v87, v33
	v_sub_f32_e32 v86, v86, v33
	v_sub_f32_e32 v85, v85, v33
	v_sub_f32_e32 v84, v84, v33
	v_sub_f32_e32 v83, v83, v33
	v_sub_f32_e32 v82, v82, v33
	v_sub_f32_e32 v81, v81, v33
	v_sub_f32_e32 v80, v80, v33
	v_sub_f32_e32 v63, v63, v33
	v_sub_f32_e32 v62, v62, v33
	v_sub_f32_e32 v61, v61, v33
	v_sub_f32_e32 v60, v60, v33
	v_sub_f32_e32 v59, v59, v33
	v_sub_f32_e32 v58, v58, v33
	v_sub_f32_e32 v57, v57, v33
	v_sub_f32_e32 v56, v56, v33
	v_sub_f32_e32 v55, v55, v33
	v_sub_f32_e32 v54, v54, v33
	v_sub_f32_e32 v53, v53, v33
	v_sub_f32_e32 v52, v52, v33
	v_sub_f32_e32 v51, v51, v33
	v_sub_f32_e32 v50, v50, v33
	v_sub_f32_e32 v49, v49, v33
	v_sub_f32_e32 v48, v48, v33
	v_pk_mul_f32 v[14:15], v[14:15], v[34:35] op_sel_hi:[1,0]
	v_pk_mul_f32 v[12:13], v[12:13], v[34:35] op_sel_hi:[1,0]
	v_pk_mul_f32 v[10:11], v[10:11], v[34:35] op_sel_hi:[1,0]
	v_pk_mul_f32 v[8:9], v[8:9], v[34:35] op_sel_hi:[1,0]
	v_pk_mul_f32 v[6:7], v[6:7], v[34:35] op_sel_hi:[1,0]
	v_pk_mul_f32 v[4:5], v[4:5], v[34:35] op_sel_hi:[1,0]
	v_pk_mul_f32 v[2:3], v[2:3], v[34:35] op_sel_hi:[1,0]
	v_pk_mul_f32 v[0:1], v[0:1], v[34:35] op_sel_hi:[1,0]
	v_pk_mul_f32 v[30:31], v[30:31], v[34:35] op_sel_hi:[1,0]
	v_pk_mul_f32 v[28:29], v[28:29], v[34:35] op_sel_hi:[1,0]
	v_pk_mul_f32 v[26:27], v[26:27], v[34:35] op_sel_hi:[1,0]
	v_pk_mul_f32 v[24:25], v[24:25], v[34:35] op_sel_hi:[1,0]
	v_pk_mul_f32 v[22:23], v[22:23], v[34:35] op_sel_hi:[1,0]
	v_pk_mul_f32 v[20:21], v[20:21], v[34:35] op_sel_hi:[1,0]
	v_pk_mul_f32 v[18:19], v[18:19], v[34:35] op_sel_hi:[1,0]
	v_pk_mul_f32 v[16:17], v[16:17], v[34:35] op_sel_hi:[1,0]
	v_mov_b32_e32 v33, v32
	v_mov_b32_e32 v34, v32
	v_mov_b32_e32 v35, v32
	v_mov_b32_e32 v36, v32
	v_mov_b32_e32 v37, v32
	v_mov_b32_e32 v38, v32
	v_mov_b32_e32 v39, v32
	v_mov_b32_e32 v40, v32
	v_mov_b32_e32 v41, v32
	v_mov_b32_e32 v42, v32
	v_mov_b32_e32 v43, v32
	v_mov_b32_e32 v44, v32
	v_mov_b32_e32 v45, v32
	v_mov_b32_e32 v46, v32
	v_mov_b32_e32 v47, v32
	v_mov_b32_e32 v64, v32
	v_mov_b32_e32 v65, v32
	v_mov_b32_e32 v66, v32
	v_mov_b32_e32 v67, v32
	v_mov_b32_e32 v68, v32
	v_mov_b32_e32 v69, v32
	v_mov_b32_e32 v70, v32
	v_mov_b32_e32 v71, v32
	v_mov_b32_e32 v72, v32
	v_mov_b32_e32 v73, v32
	v_mov_b32_e32 v74, v32
	v_mov_b32_e32 v75, v32
	v_mov_b32_e32 v76, v32
	v_mov_b32_e32 v77, v32
	v_mov_b32_e32 v78, v32
	v_mov_b32_e32 v79, v32
	s_branch .LBB0_396

; #define LAS __attribute__((address_space(3)))
; template <int DV, int PAR, bool KW = true, bool KL = true, bool VL = true>
; __device__ __forceinline__ void attn_iter_full(AttnState<DV>& S, int t, LAS unsigned char* lds) {
;     ...
;     sn0 = S.negm; sn1 = S.negm;
;     u32x4 pw[4]; float mxa = 0.f, mxb = 0.f, mx = 0.f; f32x16 ssum;
;     constexpr int PD = (DV == 64) ? 3 : 2; bf16x8 fr[PD + 1];
;     ...
; #pragma unroll
;     for (int i = 0; i < PD; ++i) fr[i] = AT_FRAG(i);
;     __builtin_amdgcn_sched_barrier(0);
; #pragma unroll
;     for (int i = 0; i < NS; ++i) {
;         if (i + PD < NS) fr[(i + PD) % (PD + 1)] = AT_FRAG(i + PD);
;         if (i == 3) {
;             if (KW) *(LAS u32x4*)(lds + AT_K0 + PAR * AT_KB + S.kl) = S.kreg;
;             LAS unsigned char* W = lds + AT_V0 + (PAR ^ 1) * AT_VB + S.vl; *(LAS u32x4*)W = S.vreg0; if (DV == 128) *(LAS u32x4*)(W + 64 * 144) = S.vreg1; }
;         if (i == 5) { if (KL) S.kreg = *(const u32x4*)(S.kg + (size_t)(t + 3) * 4096);
;             if (VL) { S.vreg0 = *(const u32x4*)(S.vg + (t + 2) * 64); if (DV == 128) S.vreg1 = *(const u32x4*)(S.vg + (size_t)64 * TK + (t + 2) * 64); } }
;         if (i < 8) { if (i & 1) sn1 = MFMA32(fr[i % (PD + 1)], S.qr[i >> 1], sn1); else sn0 = MFMA32(fr[i % (PD + 1)], S.qr[i >> 1], sn0); }
;         else { const int j = i - 8; S.o[j % NDB] = MFMA32(fr[i % (PD + 1)], __builtin_bit_cast(bf16x8, pw[j / NDB]), S.o[j % NDB]); }
; #pragma unroll
;         for (int u = 0; u < NU; ++u) {
;             if (u * NS / NU != i) continue;
;             if (u < 20) {
;                 const int q = u / 5, r = u % 5;
;                 if (r < 4) { const int e = 8 * q + 2 * r;
;                     if (e < 16) { C0[e] = fast_exp2(C0[e]); C0[e + 1] = fast_exp2(C0[e + 1]); }
;                     else { C1[e - 16] = fast_exp2(C1[e - 16]); C1[e - 15] = fast_exp2(C1[e - 15]); } }
;                 else { if (q < 2) { const int b0 = 8 * q; pw[q].x = pk2(C0[b0], C0[b0 + 1]); pw[q].y = pk2(C0[b0 + 2], C0[b0 + 3]); pw[q].z = pk2(C0[b0 + 4], C0[b0 + 5]); pw[q].w = pk2(C0[b0 + 6], C0[b0 + 7]); }
;                        else { const int b0 = 8 * (q - 2); pw[q].x = pk2(C1[b0], C1[b0 + 1]); pw[q].y = pk2(C1[b0 + 2], C1[b0 + 3]); pw[q].z = pk2(C1[b0 + 4], C1[b0 + 5]); pw[q].w = pk2(C1[b0 + 6], C1[b0 + 7]); } }
;             } else if (u == 20) { ssum = C0 + C1; }
.LBB0_414:
	ds_read_b128 v[64:67], v231 offset:9216
	ds_read_b128 v[68:71], v231 offset:13824
	s_waitcnt lgkmcnt(1)
	v_mfma_f32_32x32x16_bf16 v[144:159], v[64:67], v[174:177], v[96:111]
	ds_read_b128 v[72:75], v231 offset:9248
	v_exp_f32_e32 v64, v114
	v_exp_f32_e32 v66, v112
	v_exp_f32_e32 v67, v113
	v_exp_f32_e32 v65, v115
	s_waitcnt lgkmcnt(1)
	v_mfma_f32_32x32x16_bf16 v[128:143], v[68:71], v[174:177], v[96:111]
	ds_read_b128 v[76:79], v231 offset:13856
	v_exp_f32_e32 v68, v116
	v_exp_f32_e32 v69, v117
	s_waitcnt lgkmcnt(1)
	v_mfma_f32_32x32x16_bf16 v[144:159], v[72:75], v[170:173], v[144:159]
	ds_read_b128 v[112:115], v231 offset:9280
	v_lshl_add_u64 v[210:211], v[206:207], 0, v[160:161]
	v_lshl_add_u64 v[190:191], v[208:209], 0, v[160:161]
	v_exp_f32_e32 v70, v118
	v_exp_f32_e32 v71, v119
	s_waitcnt lgkmcnt(1)
	v_mfma_f32_32x32x16_bf16 v[128:143], v[76:79], v[170:173], v[128:143]
	ds_read_b128 v[116:119], v231 offset:13888
	s_waitcnt vmcnt(2)
	ds_write_b128 v232, v[178:181]
	s_waitcnt vmcnt(1)
	ds_write_b128 v232, v[182:185] offset:36864
	s_waitcnt vmcnt(0)
	ds_write_b128 v232, v[186:189] offset:46080
	v_cvt_pk_bf16_f32 v74, v66, v67
	v_cvt_pk_bf16_f32 v75, v64, v65
	v_cvt_pk_bf16_f32 v76, v68, v69
	v_cvt_pk_bf16_f32 v77, v70, v71
	s_waitcnt lgkmcnt(4)
	v_mfma_f32_32x32x16_bf16 v[144:159], v[112:115], v[166:169], v[144:159]
	ds_read_b128 v[234:237], v231 offset:9312
	v_exp_f32_e32 v72, v120
	v_exp_f32_e32 v73, v121
	s_mov_b32 s15, 0x10e06000
	v_add_co_u32_e32 v78, vcc, s15, v210
	ds_read_b128 v[112:115], v231 offset:13920
	s_nop 0
	v_addc_co_u32_e32 v79, vcc, 0, v211, vcc
	v_add_co_u32_e32 v212, vcc, s16, v190
	global_load_dwordx4 v[178:181], v[78:79], off
	s_nop 0
	v_addc_co_u32_e32 v213, vcc, 0, v191, vcc
	v_add_co_u32_e32 v214, vcc, s17, v190
	global_load_dwordx4 v[182:185], v[212:213], off offset:256
	s_nop 0
	v_addc_co_u32_e32 v215, vcc, 0, v191, vcc
	global_load_dwordx4 v[186:189], v[214:215], off offset:256
	s_waitcnt lgkmcnt(5)
	v_mfma_f32_32x32x16_bf16 v[128:143], v[116:119], v[166:169], v[128:143]
	v_exp_f32_e32 v190, v122
	v_exp_f32_e32 v191, v123
	s_waitcnt lgkmcnt(1)
	v_mfma_f32_32x32x16_bf16 v[144:159], v[234:237], v[162:165], v[144:159]
	ds_read_b128 v[116:119], v230 offset:18432
	v_exp_f32_e32 v124, v124
	v_exp_f32_e32 v125, v125
	s_waitcnt lgkmcnt(1)
	v_mfma_f32_32x32x16_bf16 v[128:143], v[112:115], v[162:165], v[128:143]
	ds_read_b128 v[120:123], v230 offset:23040
	v_exp_f32_e32 v126, v126
	v_exp_f32_e32 v127, v127
	s_waitcnt lgkmcnt(1)
	v_mfma_f32_32x32x16_bf16 v[48:63], v[116:119], v[74:77], v[48:63]
	ds_read_b128 v[112:115], v230 offset:27648
	v_cvt_pk_bf16_f32 v116, v72, v73
	v_cvt_pk_bf16_f32 v117, v190, v191
	v_cvt_pk_bf16_f32 v118, v124, v125
	v_cvt_pk_bf16_f32 v119, v126, v127
	v_exp_f32_e32 v192, v80
	v_exp_f32_e32 v193, v81
	s_waitcnt lgkmcnt(1)
	v_mfma_f32_32x32x16_bf16 v[32:47], v[120:123], v[74:77], v[32:47]
	ds_read_b128 v[78:81], v230 offset:32256
	v_exp_f32_e32 v196, v82
	v_exp_f32_e32 v197, v83
	s_waitcnt lgkmcnt(1)
	v_mfma_f32_32x32x16_bf16 v[16:31], v[112:115], v[74:77], v[16:31]
	ds_read_b128 v[120:123], v230 offset:18464
	v_exp_f32_e32 v198, v84
	v_exp_f32_e32 v199, v85
	s_waitcnt lgkmcnt(1)
	v_mfma_f32_32x32x16_bf16 v[0:15], v[78:81], v[74:77], v[0:15]
	ds_read_b128 v[82:85], v230 offset:23072
	v_exp_f32_e32 v234, v86
	v_exp_f32_e32 v235, v87
	s_waitcnt lgkmcnt(1)
	v_mfma_f32_32x32x16_bf16 v[48:63], v[120:123], v[116:119], v[48:63]
	ds_read_b128 v[74:77], v230 offset:27680
	v_cvt_pk_bf16_f32 v78, v192, v193
	v_cvt_pk_bf16_f32 v79, v196, v197
	v_cvt_pk_bf16_f32 v80, v198, v199
	v_cvt_pk_bf16_f32 v81, v234, v235
	s_waitcnt lgkmcnt(1)
	v_mfma_f32_32x32x16_bf16 v[32:47], v[82:85], v[116:119], v[32:47]
	ds_read_b128 v[112:115], v230 offset:32288
	v_exp_f32_e32 v120, v88
	v_exp_f32_e32 v121, v89
	s_waitcnt lgkmcnt(1)
	v_mfma_f32_32x32x16_bf16 v[16:31], v[74:77], v[116:119], v[16:31]
	ds_read_b128 v[82:85], v230 offset:18496
	v_exp_f32_e32 v122, v90
	v_exp_f32_e32 v123, v91
	s_waitcnt lgkmcnt(1)
	v_mfma_f32_32x32x16_bf16 v[0:15], v[112:115], v[116:119], v[0:15]
	ds_read_b128 v[74:77], v230 offset:23104
	v_exp_f32_e32 v112, v92
	v_exp_f32_e32 v113, v93
	s_waitcnt lgkmcnt(1)
	v_mfma_f32_32x32x16_bf16 v[48:63], v[82:85], v[78:81], v[48:63]
	ds_read_b128 v[86:89], v230 offset:27712
	v_exp_f32_e32 v94, v94
	v_exp_f32_e32 v95, v95
	v_cvt_pk_bf16_f32 v82, v120, v121
	v_cvt_pk_bf16_f32 v83, v122, v123
	v_cvt_pk_bf16_f32 v84, v112, v113
	v_cvt_pk_bf16_f32 v85, v94, v95
	s_waitcnt lgkmcnt(1)
	v_mfma_f32_32x32x16_bf16 v[32:47], v[74:77], v[78:81], v[32:47]
	ds_read_b128 v[90:93], v230 offset:32320
	v_add_f32_e64 v74, v112, v124
	v_add_f32_e64 v75, v113, v125
	v_add_f32_e64 v76, v94, v126
	v_add_f32_e64 v77, v95, v127
	v_pk_add_f32 v[94:95], v[122:123], v[190:191]
	v_pk_add_f32 v[72:73], v[120:121], v[72:73]
	v_pk_add_f32 v[68:69], v[198:199], v[68:69]
	v_pk_add_f32 v[112:113], v[192:193], v[66:67]
	v_pk_add_f32 v[70:71], v[234:235], v[70:71]
	v_pk_add_f32 v[114:115], v[196:197], v[64:65]
	s_waitcnt lgkmcnt(1)
	v_mfma_f32_32x32x16_bf16 v[16:31], v[86:89], v[78:81], v[16:31]
	v_add_f32_e64 v70, v114, v70
	v_add_f32_e64 v71, v115, v71
	v_add_f32_e64 v68, v112, v68
	v_add_f32_e64 v69, v113, v69
	v_add_f32_e64 v70, v94, v70
	v_add_f32_e64 v71, v95, v71
	v_pk_add_f32 v[68:69], v[72:73], v[68:69]
	ds_read_b128 v[64:67], v230 offset:18528
	v_pk_add_f32 v[70:71], v[76:77], v[70:71]
	v_pk_add_f32 v[68:69], v[74:75], v[68:69]
	s_nop 0
	v_pk_mov_b32 v[72:73], v[68:69], v[70:71] op_sel:[1,0]
	v_mov_b32_e32 v69, v71
	v_pk_add_f32 v[68:69], v[72:73], v[68:69]
	s_nop 0
	v_add_f32_e32 v68, v68, v69
	v_add_f32_e32 v234, v216, v68
	s_waitcnt lgkmcnt(1)
	v_mfma_f32_32x32x16_bf16 v[0:15], v[90:93], v[78:81], v[0:15]
	ds_read_b128 v[68:71], v230 offset:23136
	v_max3_f32 v72, v144, v145, v128
	v_max3_f32 v76, v146, v147, v129
	v_max3_f32 v77, v72, v130, v131
	s_waitcnt lgkmcnt(1)
	v_mfma_f32_32x32x16_bf16 v[48:63], v[64:67], v[82:85], v[48:63]
	ds_read_b128 v[72:75], v230 offset:27744
	v_max3_f32 v64, v77, v148, v149
	v_max3_f32 v65, v76, v150, v151
	v_max3_f32 v76, v64, v132, v133
	v_max3_f32 v77, v65, v134, v135
	s_waitcnt lgkmcnt(1)
	v_mfma_f32_32x32x16_bf16 v[32:47], v[68:71], v[82:85], v[32:47]
	ds_read_b128 v[64:67], v230 offset:32352
	v_max3_f32 v68, v76, v152, v153
	v_max3_f32 v69, v77, v154, v155
	v_max3_f32 v68, v68, v136, v137
	v_max3_f32 v69, v69, v138, v139
	s_waitcnt lgkmcnt(1)
	v_mfma_f32_32x32x16_bf16 v[16:31], v[72:75], v[82:85], v[16:31]
	v_max3_f32 v68, v68, v156, v157
	v_max3_f32 v69, v69, v158, v159
	v_max3_f32 v68, v68, v140, v141
	v_max3_f32 v69, v69, v142, v143
	s_waitcnt lgkmcnt(0)
	v_mfma_f32_32x32x16_bf16 v[0:15], v[64:67], v[82:85], v[0:15]
	v_max_f32_e32 v64, v68, v69
	v_mov_b32_e32 v65, v64
	s_nop 1
	v_permlane32_swap_b32_e32 v64, v65
	v_max_f32_e32 v64, v64, v65
	s_nop 0
	v_cmp_lt_f32_e32 vcc, s3, v64
	s_cbranch_vccz .LBB0_416
; __device__ __forceinline__ float fast_exp2(float x) { return __builtin_amdgcn_exp2f(x); }
; template <int DV, int PAR, bool KW = true, bool KL = true, bool VL = true>
; __device__ __forceinline__ void attn_iter_full(AttnState<DV>& S, int t, LAS unsigned char* lds) {
;     ...
;     if (__any(mx > 8.0f)) {
;         const float dl = fmaxf(mx, 0.f), alpha = fast_exp2(-dl);
;         S.mrun += dl; S.lsum *= alpha;
; #pragma unroll
;         for (int i = 0; i < 16; ++i) { sn0[i] -= dl; sn1[i] -= dl; S.negm[i] = -S.mrun; }
; #pragma unroll
;         for (int d = 0; d < NDB; ++d)
; #pragma unroll
;             for (int i = 0; i < 16; ++i) S.o[d][i] *= alpha;
;     }
	v_max_f32_e32 v64, v64, v64
	v_max_f32_e32 v66, 0, v64
	v_exp_f32_e64 v68, -v66
	v_add_f32_e32 v233, v233, v66
	v_xor_b32_e32 v64, 0x80000000, v233
	v_pk_add_f32 v[144:145], v[144:145], v[66:67] op_sel_hi:[1,0] neg_lo:[0,1] neg_hi:[0,1]
	v_mul_f32_e32 v234, v234, v68
	v_pk_add_f32 v[128:129], v[128:129], v[66:67] op_sel_hi:[1,0] neg_lo:[0,1] neg_hi:[0,1]
	v_pk_add_f32 v[146:147], v[146:147], v[66:67] op_sel_hi:[1,0] neg_lo:[0,1] neg_hi:[0,1]
	v_pk_add_f32 v[130:131], v[130:131], v[66:67] op_sel_hi:[1,0] neg_lo:[0,1] neg_hi:[0,1]
	v_pk_add_f32 v[148:149], v[148:149], v[66:67] op_sel_hi:[1,0] neg_lo:[0,1] neg_hi:[0,1]
	v_pk_add_f32 v[132:133], v[132:133], v[66:67] op_sel_hi:[1,0] neg_lo:[0,1] neg_hi:[0,1]
	v_pk_add_f32 v[150:151], v[150:151], v[66:67] op_sel_hi:[1,0] neg_lo:[0,1] neg_hi:[0,1]
	v_pk_add_f32 v[134:135], v[134:135], v[66:67] op_sel_hi:[1,0] neg_lo:[0,1] neg_hi:[0,1]
	v_pk_add_f32 v[152:153], v[152:153], v[66:67] op_sel_hi:[1,0] neg_lo:[0,1] neg_hi:[0,1]
	v_pk_add_f32 v[136:137], v[136:137], v[66:67] op_sel_hi:[1,0] neg_lo:[0,1] neg_hi:[0,1]
	v_pk_add_f32 v[154:155], v[154:155], v[66:67] op_sel_hi:[1,0] neg_lo:[0,1] neg_hi:[0,1]
	v_pk_add_f32 v[138:139], v[138:139], v[66:67] op_sel_hi:[1,0] neg_lo:[0,1] neg_hi:[0,1]
	v_pk_add_f32 v[156:157], v[156:157], v[66:67] op_sel_hi:[1,0] neg_lo:[0,1] neg_hi:[0,1]
	v_pk_add_f32 v[140:141], v[140:141], v[66:67] op_sel_hi:[1,0] neg_lo:[0,1] neg_hi:[0,1]
	v_pk_add_f32 v[158:159], v[158:159], v[66:67] op_sel_hi:[1,0] neg_lo:[0,1] neg_hi:[0,1]
	v_pk_add_f32 v[142:143], v[142:143], v[66:67] op_sel_hi:[1,0] neg_lo:[0,1] neg_hi:[0,1]
	v_pk_mul_f32 v[62:63], v[62:63], v[68:69] op_sel_hi:[1,0]
	v_pk_mul_f32 v[60:61], v[60:61], v[68:69] op_sel_hi:[1,0]
	v_pk_mul_f32 v[58:59], v[58:59], v[68:69] op_sel_hi:[1,0]
	v_pk_mul_f32 v[56:57], v[56:57], v[68:69] op_sel_hi:[1,0]
	v_pk_mul_f32 v[54:55], v[54:55], v[68:69] op_sel_hi:[1,0]
	v_pk_mul_f32 v[52:53], v[52:53], v[68:69] op_sel_hi:[1,0]
	v_pk_mul_f32 v[50:51], v[50:51], v[68:69] op_sel_hi:[1,0]
	v_pk_mul_f32 v[48:49], v[48:49], v[68:69] op_sel_hi:[1,0]
	v_pk_mul_f32 v[46:47], v[46:47], v[68:69] op_sel_hi:[1,0]
	v_pk_mul_f32 v[44:45], v[44:45], v[68:69] op_sel_hi:[1,0]
	v_pk_mul_f32 v[42:43], v[42:43], v[68:69] op_sel_hi:[1,0]
	v_pk_mul_f32 v[40:41], v[40:41], v[68:69] op_sel_hi:[1,0]
	v_pk_mul_f32 v[38:39], v[38:39], v[68:69] op_sel_hi:[1,0]
	v_pk_mul_f32 v[36:37], v[36:37], v[68:69] op_sel_hi:[1,0]
	v_pk_mul_f32 v[34:35], v[34:35], v[68:69] op_sel_hi:[1,0]
	v_pk_mul_f32 v[32:33], v[32:33], v[68:69] op_sel_hi:[1,0]
	v_pk_mul_f32 v[30:31], v[30:31], v[68:69] op_sel_hi:[1,0]
	v_pk_mul_f32 v[28:29], v[28:29], v[68:69] op_sel_hi:[1,0]
	v_pk_mul_f32 v[26:27], v[26:27], v[68:69] op_sel_hi:[1,0]
	v_pk_mul_f32 v[24:25], v[24:25], v[68:69] op_sel_hi:[1,0]
	v_pk_mul_f32 v[22:23], v[22:23], v[68:69] op_sel_hi:[1,0]
	v_pk_mul_f32 v[20:21], v[20:21], v[68:69] op_sel_hi:[1,0]
	v_pk_mul_f32 v[18:19], v[18:19], v[68:69] op_sel_hi:[1,0]
	v_pk_mul_f32 v[16:17], v[16:17], v[68:69] op_sel_hi:[1,0]
	v_pk_mul_f32 v[14:15], v[14:15], v[68:69] op_sel_hi:[1,0]
	v_pk_mul_f32 v[12:13], v[12:13], v[68:69] op_sel_hi:[1,0]
	v_pk_mul_f32 v[10:11], v[10:11], v[68:69] op_sel_hi:[1,0]
	v_pk_mul_f32 v[8:9], v[8:9], v[68:69] op_sel_hi:[1,0]
	v_pk_mul_f32 v[6:7], v[6:7], v[68:69] op_sel_hi:[1,0]
	v_pk_mul_f32 v[4:5], v[4:5], v[68:69] op_sel_hi:[1,0]
	v_pk_mul_f32 v[2:3], v[2:3], v[68:69] op_sel_hi:[1,0]
	v_pk_mul_f32 v[0:1], v[0:1], v[68:69] op_sel_hi:[1,0]
	v_mov_b32_e32 v65, v64
	v_mov_b32_e32 v66, v64
	v_mov_b32_e32 v67, v64
	v_mov_b32_e32 v68, v64
	v_mov_b32_e32 v69, v64
	v_mov_b32_e32 v70, v64
	v_mov_b32_e32 v71, v64
	v_mov_b32_e32 v72, v64
	v_mov_b32_e32 v73, v64
	v_mov_b32_e32 v74, v64
	v_mov_b32_e32 v75, v64
	v_mov_b32_e32 v76, v64
	v_mov_b32_e32 v77, v64
	v_mov_b32_e32 v78, v64
	v_mov_b32_e32 v79, v64
	v_mov_b32_e32 v96, v64
	v_mov_b32_e32 v97, v64
	v_mov_b32_e32 v98, v64
	v_mov_b32_e32 v99, v64
	v_mov_b32_e32 v100, v64
	v_mov_b32_e32 v101, v64
	v_mov_b32_e32 v102, v64
	v_mov_b32_e32 v103, v64
	v_mov_b32_e32 v104, v64
	v_mov_b32_e32 v105, v64
	v_mov_b32_e32 v106, v64
	v_mov_b32_e32 v107, v64
	v_mov_b32_e32 v108, v64
	v_mov_b32_e32 v109, v64
	v_mov_b32_e32 v110, v64
	v_mov_b32_e32 v111, v64
	s_branch .LBB0_417
; #define LAS __attribute__((address_space(3)))
; template <int DV, int PAR, bool KW = true, bool KL = true, bool VL = true>
; __device__ __forceinline__ void attn_iter_full(AttnState<DV>& S, int t, LAS unsigned char* lds) {
;     ...
;     u32x4 pw[4]; float mxa = 0.f, mxb = 0.f, mx = 0.f; f32x16 ssum;
;     constexpr int PD = (DV == 64) ? 3 : 2; bf16x8 fr[PD + 1];
;     ...
; #pragma unroll
;     for (int i = 0; i < PD; ++i) fr[i] = AT_FRAG(i);
;     __builtin_amdgcn_sched_barrier(0);
; #pragma unroll
;     for (int i = 0; i < NS; ++i) {
;         if (i + PD < NS) fr[(i + PD) % (PD + 1)] = AT_FRAG(i + PD);
;         if (i == 3) {
;             if (KW) *(LAS u32x4*)(lds + AT_K0 + PAR * AT_KB + S.kl) = S.kreg;
;             LAS unsigned char* W = lds + AT_V0 + (PAR ^ 1) * AT_VB + S.vl; *(LAS u32x4*)W = S.vreg0; if (DV == 128) *(LAS u32x4*)(W + 64 * 144) = S.vreg1; }
;         if (i == 5) { if (KL) S.kreg = *(const u32x4*)(S.kg + (size_t)(t + 3) * 4096);
;             if (VL) { S.vreg0 = *(const u32x4*)(S.vg + (t + 2) * 64); if (DV == 128) S.vreg1 = *(const u32x4*)(S.vg + (size_t)64 * TK + (t + 2) * 64); } }
;         if (i < 8) { if (i & 1) sn1 = MFMA32(fr[i % (PD + 1)], S.qr[i >> 1], sn1); else sn0 = MFMA32(fr[i % (PD + 1)], S.qr[i >> 1], sn0); }
;         else { const int j = i - 8; S.o[j % NDB] = MFMA32(fr[i % (PD + 1)], __builtin_bit_cast(bf16x8, pw[j / NDB]), S.o[j % NDB]); }
; #pragma unroll
;         for (int u = 0; u < NU; ++u) {
;             if (u * NS / NU != i) continue;
;             if (u < 20) {
;                 const int q = u / 5, r = u % 5;
;                 if (r < 4) { const int e = 8 * q + 2 * r;
;                     if (e < 16) { C0[e] = fast_exp2(C0[e]); C0[e + 1] = fast_exp2(C0[e + 1]); }
;                     else { C1[e - 16] = fast_exp2(C1[e - 16]); C1[e - 15] = fast_exp2(C1[e - 15]); } }
;                 else { if (q < 2) { const int b0 = 8 * q; pw[q].x = pk2(C0[b0], C0[b0 + 1]); pw[q].y = pk2(C0[b0 + 2], C0[b0 + 3]); pw[q].z = pk2(C0[b0 + 4], C0[b0 + 5]); pw[q].w = pk2(C0[b0 + 6], C0[b0 + 7]); }
;                        else { const int b0 = 8 * (q - 2); pw[q].x = pk2(C1[b0], C1[b0 + 1]); pw[q].y = pk2(C1[b0 + 2], C1[b0 + 3]); pw[q].z = pk2(C1[b0 + 4], C1[b0 + 5]); pw[q].w = pk2(C1[b0 + 6], C1[b0 + 7]); } }
;             } else if (u == 20) { ssum = C0 + C1; }
.LBB0_416:
.LBB0_417:
	s_barrier
	ds_read_b128 v[80:83], v231
	ds_read_b128 v[242:245], v231 offset:4608
	s_waitcnt lgkmcnt(1)
	v_mfma_f32_32x32x16_bf16 v[112:127], v[80:83], v[174:177], v[96:111]
	ds_read_b128 v[246:249], v231 offset:32
	v_exp_f32_e32 v216, v144
	v_exp_f32_e32 v217, v145
	v_exp_f32_e32 v144, v146
	v_exp_f32_e32 v145, v147
	s_waitcnt lgkmcnt(1)
	v_mfma_f32_32x32x16_bf16 v[80:95], v[242:245], v[174:177], v[96:111]
	ds_read_b128 v[190:193], v231 offset:4640
	v_exp_f32_e32 v146, v148
	v_exp_f32_e32 v147, v149
	s_waitcnt lgkmcnt(1)
	v_mfma_f32_32x32x16_bf16 v[112:127], v[246:249], v[170:173], v[112:127]
	ds_read_b128 v[242:245], v231 offset:64
	v_exp_f32_e32 v148, v150
	v_exp_f32_e32 v149, v151
	s_waitcnt lgkmcnt(1)
	v_mfma_f32_32x32x16_bf16 v[80:95], v[190:193], v[170:173], v[80:95]
	ds_read_b128 v[246:249], v231 offset:4672
	s_waitcnt vmcnt(2)
	ds_write_b128 v232, v[178:181] offset:9216
	s_waitcnt vmcnt(1)
	ds_write_b128 v232, v[182:185] offset:18432
	s_waitcnt vmcnt(0)
	ds_write_b128 v232, v[186:189] offset:27648
	v_cvt_pk_bf16_f32 v196, v216, v217
	v_cvt_pk_bf16_f32 v197, v144, v145
	v_cvt_pk_bf16_f32 v198, v146, v147
	v_cvt_pk_bf16_f32 v199, v148, v149
	s_waitcnt lgkmcnt(4)
	v_mfma_f32_32x32x16_bf16 v[112:127], v[242:245], v[166:169], v[112:127]
	ds_read_b128 v[190:193], v231 offset:96
	v_exp_f32_e32 v150, v152
	v_exp_f32_e32 v151, v153
	s_mov_b32 s15, 0x10e08000
	v_add_co_u32_e32 v152, vcc, s15, v210
	ds_read_b128 v[242:245], v231 offset:4704
	s_nop 0
	v_addc_co_u32_e32 v153, vcc, 0, v211, vcc
	global_load_dwordx4 v[178:181], v[152:153], off
	global_load_dwordx4 v[182:185], v[212:213], off offset:384
	global_load_dwordx4 v[186:189], v[214:215], off offset:384
	s_waitcnt lgkmcnt(5)
	v_mfma_f32_32x32x16_bf16 v[80:95], v[246:249], v[166:169], v[80:95]
	v_exp_f32_e32 v214, v154
	v_exp_f32_e32 v215, v155
	s_waitcnt lgkmcnt(1)
	v_mfma_f32_32x32x16_bf16 v[112:127], v[190:193], v[162:165], v[112:127]
	ds_read_b128 v[152:155], v230 offset:36864
	v_exp_f32_e32 v236, v156
	v_exp_f32_e32 v237, v157
	s_waitcnt lgkmcnt(1)
	v_mfma_f32_32x32x16_bf16 v[80:95], v[242:245], v[162:165], v[80:95]
	ds_read_b128 v[190:193], v230 offset:41472
	v_exp_f32_e32 v242, v158
	v_exp_f32_e32 v243, v159
	s_waitcnt lgkmcnt(1)
	v_mfma_f32_32x32x16_bf16 v[48:63], v[152:155], v[196:199], v[48:63]
	ds_read_b128 v[156:159], v230 offset:46080
	v_cvt_pk_bf16_f32 v152, v150, v151
	v_cvt_pk_bf16_f32 v153, v214, v215
	v_cvt_pk_bf16_f32 v154, v236, v237
	v_cvt_pk_bf16_f32 v155, v242, v243
	v_exp_f32_e32 v244, v128
	v_exp_f32_e32 v245, v129
	s_waitcnt lgkmcnt(1)
	v_mfma_f32_32x32x16_bf16 v[32:47], v[190:193], v[196:199], v[32:47]
	ds_read_b128 v[210:213], v230 offset:50688
	v_exp_f32_e32 v246, v130
	v_exp_f32_e32 v247, v131
	s_waitcnt lgkmcnt(1)
	v_mfma_f32_32x32x16_bf16 v[16:31], v[156:159], v[196:199], v[16:31]
	ds_read_b128 v[128:131], v230 offset:36896
	v_exp_f32_e32 v248, v132
	v_exp_f32_e32 v249, v133
	s_waitcnt lgkmcnt(1)
	v_mfma_f32_32x32x16_bf16 v[0:15], v[210:213], v[196:199], v[0:15]
	ds_read_b128 v[156:159], v230 offset:41504
	v_exp_f32_e32 v196, v134
	v_exp_f32_e32 v197, v135
	s_waitcnt lgkmcnt(1)
	v_mfma_f32_32x32x16_bf16 v[48:63], v[128:131], v[152:155], v[48:63]
	ds_read_b128 v[132:135], v230 offset:46112
	v_cvt_pk_bf16_f32 v128, v244, v245
	v_cvt_pk_bf16_f32 v129, v246, v247
	v_cvt_pk_bf16_f32 v130, v248, v249
	v_cvt_pk_bf16_f32 v131, v196, v197
	s_waitcnt lgkmcnt(1)
	v_mfma_f32_32x32x16_bf16 v[32:47], v[156:159], v[152:155], v[32:47]
	ds_read_b128 v[190:193], v230 offset:50720
	v_exp_f32_e32 v198, v136
	v_exp_f32_e32 v199, v137
	s_waitcnt lgkmcnt(1)
	v_mfma_f32_32x32x16_bf16 v[16:31], v[132:135], v[152:155], v[16:31]
	ds_read_b128 v[156:159], v230 offset:36928
	v_exp_f32_e32 v210, v138
	v_exp_f32_e32 v211, v139
	s_waitcnt lgkmcnt(1)
	v_mfma_f32_32x32x16_bf16 v[0:15], v[190:193], v[152:155], v[0:15]
	ds_read_b128 v[132:135], v230 offset:41536
	v_exp_f32_e32 v190, v140
	v_exp_f32_e32 v191, v141
	s_waitcnt lgkmcnt(1)
	v_mfma_f32_32x32x16_bf16 v[48:63], v[156:159], v[128:131], v[48:63]
	ds_read_b128 v[136:139], v230 offset:46144
	v_exp_f32_e32 v156, v142
	v_exp_f32_e32 v157, v143
	v_cvt_pk_bf16_f32 v140, v198, v199
	v_cvt_pk_bf16_f32 v141, v210, v211
	v_cvt_pk_bf16_f32 v142, v190, v191
	v_cvt_pk_bf16_f32 v143, v156, v157
	s_waitcnt lgkmcnt(1)
	v_mfma_f32_32x32x16_bf16 v[32:47], v[132:135], v[128:131], v[32:47]
	ds_read_b128 v[152:155], v230 offset:50752
	v_add_f32_e64 v158, v190, v236
	v_add_f32_e64 v159, v191, v237
	v_add_f32_e64 v156, v156, v242
	v_add_f32_e64 v157, v157, v243
	v_pk_add_f32 v[190:191], v[210:211], v[214:215]
	v_pk_add_f32 v[150:151], v[198:199], v[150:151]
	v_pk_add_f32 v[146:147], v[248:249], v[146:147]
	v_pk_add_f32 v[192:193], v[244:245], v[216:217]
	v_pk_add_f32 v[148:149], v[196:197], v[148:149]
	v_pk_add_f32 v[144:145], v[246:247], v[144:145]
	s_waitcnt lgkmcnt(1)
	v_mfma_f32_32x32x16_bf16 v[16:31], v[136:139], v[128:131], v[16:31]
	v_add_f32_e64 v136, v144, v148
	v_add_f32_e64 v137, v145, v149
	v_add_f32_e64 v138, v192, v146
	v_add_f32_e64 v139, v193, v147
	v_add_f32_e64 v136, v190, v136
	v_add_f32_e64 v137, v191, v137
	v_pk_add_f32 v[138:139], v[150:151], v[138:139]
	v_pk_add_f32 v[136:137], v[156:157], v[136:137]
	v_pk_add_f32 v[138:139], v[158:159], v[138:139]
	ds_read_b128 v[132:135], v230 offset:36960
	v_pk_mov_b32 v[144:145], v[138:139], v[136:137] op_sel:[1,0]
	v_mov_b32_e32 v139, v137
	v_pk_add_f32 v[136:137], v[144:145], v[138:139]
	s_nop 0
	v_add_f32_e32 v136, v136, v137
	v_add_f32_e32 v216, v234, v136
	s_waitcnt lgkmcnt(1)
	v_mfma_f32_32x32x16_bf16 v[0:15], v[152:155], v[128:131], v[0:15]
	ds_read_b128 v[136:139], v230 offset:41568
	v_max3_f32 v128, v112, v113, v80
	v_max3_f32 v144, v114, v115, v81
	v_max3_f32 v145, v128, v82, v83
	s_waitcnt lgkmcnt(1)
	v_mfma_f32_32x32x16_bf16 v[48:63], v[132:135], v[140:143], v[48:63]
	ds_read_b128 v[128:131], v230 offset:46176
	v_max3_f32 v132, v145, v116, v117
	v_max3_f32 v133, v144, v118, v119
	v_max3_f32 v144, v132, v84, v85
	v_max3_f32 v145, v133, v86, v87
	s_waitcnt lgkmcnt(1)
	v_mfma_f32_32x32x16_bf16 v[32:47], v[136:139], v[140:143], v[32:47]
	ds_read_b128 v[132:135], v230 offset:50784
	v_max3_f32 v136, v144, v120, v121
	v_max3_f32 v137, v145, v122, v123
	v_max3_f32 v136, v136, v88, v89
	v_max3_f32 v137, v137, v90, v91
	s_waitcnt lgkmcnt(1)
	v_mfma_f32_32x32x16_bf16 v[16:31], v[128:131], v[140:143], v[16:31]
	v_max3_f32 v128, v136, v124, v125
	v_max3_f32 v129, v137, v126, v127
	v_max3_f32 v128, v128, v92, v93
	v_max3_f32 v129, v129, v94, v95
	s_waitcnt lgkmcnt(0)
	v_mfma_f32_32x32x16_bf16 v[0:15], v[132:135], v[140:143], v[0:15]
	v_max_f32_e32 v128, v128, v129
	v_mov_b32_e32 v129, v128
	s_nop 1
	v_permlane32_swap_b32_e32 v128, v129
	v_max_f32_e32 v128, v128, v129
	s_nop 0
	v_cmp_lt_f32_e32 vcc, s3, v128
	s_cbranch_vccz .LBB0_413
; __device__ __forceinline__ float fast_exp2(float x) { return __builtin_amdgcn_exp2f(x); }
; template <int DV, int PAR, bool KW = true, bool KL = true, bool VL = true>
; __device__ __forceinline__ void attn_iter_full(AttnState<DV>& S, int t, LAS unsigned char* lds) {
;     ...
;     if (__any(mx > 8.0f)) {
;         const float dl = fmaxf(mx, 0.f), alpha = fast_exp2(-dl);
;         S.mrun += dl; S.lsum *= alpha;
; #pragma unroll
;         for (int i = 0; i < 16; ++i) { sn0[i] -= dl; sn1[i] -= dl; S.negm[i] = -S.mrun; }
; #pragma unroll
;         for (int d = 0; d < NDB; ++d)
; #pragma unroll
;             for (int i = 0; i < 16; ++i) S.o[d][i] *= alpha;
;     }
	v_max_f32_e32 v64, v128, v128
	v_max_f32_e32 v65, 0, v64
	v_exp_f32_e64 v66, -v65
	v_add_f32_e32 v233, v233, v65
	v_xor_b32_e32 v64, 0x80000000, v233
	v_sub_f32_e32 v127, v127, v65
	v_mul_f32_e32 v216, v216, v66
	v_sub_f32_e32 v126, v126, v65
	v_sub_f32_e32 v125, v125, v65
	v_sub_f32_e32 v124, v124, v65
	v_sub_f32_e32 v123, v123, v65
	v_sub_f32_e32 v122, v122, v65
	v_sub_f32_e32 v121, v121, v65
	v_sub_f32_e32 v120, v120, v65
	v_sub_f32_e32 v119, v119, v65
	v_sub_f32_e32 v118, v118, v65
	v_sub_f32_e32 v117, v117, v65
	v_sub_f32_e32 v116, v116, v65
	v_sub_f32_e32 v115, v115, v65
	v_sub_f32_e32 v114, v114, v65
	v_sub_f32_e32 v113, v113, v65
	v_sub_f32_e32 v112, v112, v65
	v_sub_f32_e32 v95, v95, v65
	v_sub_f32_e32 v94, v94, v65
	v_sub_f32_e32 v93, v93, v65
	v_sub_f32_e32 v92, v92, v65
	v_sub_f32_e32 v91, v91, v65
	v_sub_f32_e32 v90, v90, v65
	v_sub_f32_e32 v89, v89, v65
	v_sub_f32_e32 v88, v88, v65
	v_sub_f32_e32 v87, v87, v65
	v_sub_f32_e32 v86, v86, v65
	v_sub_f32_e32 v85, v85, v65
	v_sub_f32_e32 v84, v84, v65
	v_sub_f32_e32 v83, v83, v65
	v_sub_f32_e32 v82, v82, v65
	v_sub_f32_e32 v81, v81, v65
	v_sub_f32_e32 v80, v80, v65
	v_pk_mul_f32 v[62:63], v[62:63], v[66:67] op_sel_hi:[1,0]
	v_pk_mul_f32 v[60:61], v[60:61], v[66:67] op_sel_hi:[1,0]
	v_pk_mul_f32 v[58:59], v[58:59], v[66:67] op_sel_hi:[1,0]
	v_pk_mul_f32 v[56:57], v[56:57], v[66:67] op_sel_hi:[1,0]
	v_pk_mul_f32 v[54:55], v[54:55], v[66:67] op_sel_hi:[1,0]
	v_pk_mul_f32 v[52:53], v[52:53], v[66:67] op_sel_hi:[1,0]
	v_pk_mul_f32 v[50:51], v[50:51], v[66:67] op_sel_hi:[1,0]
	v_pk_mul_f32 v[48:49], v[48:49], v[66:67] op_sel_hi:[1,0]
	v_pk_mul_f32 v[46:47], v[46:47], v[66:67] op_sel_hi:[1,0]
	v_pk_mul_f32 v[44:45], v[44:45], v[66:67] op_sel_hi:[1,0]
	v_pk_mul_f32 v[42:43], v[42:43], v[66:67] op_sel_hi:[1,0]
	v_pk_mul_f32 v[40:41], v[40:41], v[66:67] op_sel_hi:[1,0]
	v_pk_mul_f32 v[38:39], v[38:39], v[66:67] op_sel_hi:[1,0]
	v_pk_mul_f32 v[36:37], v[36:37], v[66:67] op_sel_hi:[1,0]
	v_pk_mul_f32 v[34:35], v[34:35], v[66:67] op_sel_hi:[1,0]
	v_pk_mul_f32 v[32:33], v[32:33], v[66:67] op_sel_hi:[1,0]
	v_pk_mul_f32 v[30:31], v[30:31], v[66:67] op_sel_hi:[1,0]
	v_pk_mul_f32 v[28:29], v[28:29], v[66:67] op_sel_hi:[1,0]
	v_pk_mul_f32 v[26:27], v[26:27], v[66:67] op_sel_hi:[1,0]
	v_pk_mul_f32 v[24:25], v[24:25], v[66:67] op_sel_hi:[1,0]
	v_pk_mul_f32 v[22:23], v[22:23], v[66:67] op_sel_hi:[1,0]
	v_pk_mul_f32 v[20:21], v[20:21], v[66:67] op_sel_hi:[1,0]
	v_pk_mul_f32 v[18:19], v[18:19], v[66:67] op_sel_hi:[1,0]
	v_pk_mul_f32 v[16:17], v[16:17], v[66:67] op_sel_hi:[1,0]
	v_pk_mul_f32 v[14:15], v[14:15], v[66:67] op_sel_hi:[1,0]
	v_pk_mul_f32 v[12:13], v[12:13], v[66:67] op_sel_hi:[1,0]
	v_pk_mul_f32 v[10:11], v[10:11], v[66:67] op_sel_hi:[1,0]
	v_pk_mul_f32 v[8:9], v[8:9], v[66:67] op_sel_hi:[1,0]
	v_pk_mul_f32 v[6:7], v[6:7], v[66:67] op_sel_hi:[1,0]
	v_pk_mul_f32 v[4:5], v[4:5], v[66:67] op_sel_hi:[1,0]
	v_pk_mul_f32 v[2:3], v[2:3], v[66:67] op_sel_hi:[1,0]
	v_pk_mul_f32 v[0:1], v[0:1], v[66:67] op_sel_hi:[1,0]
	v_mov_b32_e32 v65, v64
	v_mov_b32_e32 v66, v64
	v_mov_b32_e32 v67, v64
	v_mov_b32_e32 v68, v64
	v_mov_b32_e32 v69, v64
	v_mov_b32_e32 v70, v64
	v_mov_b32_e32 v71, v64
	v_mov_b32_e32 v72, v64
	v_mov_b32_e32 v73, v64
	v_mov_b32_e32 v74, v64
	v_mov_b32_e32 v75, v64
	v_mov_b32_e32 v76, v64
	v_mov_b32_e32 v77, v64
	v_mov_b32_e32 v78, v64
	v_mov_b32_e32 v79, v64
	v_mov_b32_e32 v96, v64
	v_mov_b32_e32 v97, v64
	v_mov_b32_e32 v98, v64
	v_mov_b32_e32 v99, v64
	v_mov_b32_e32 v100, v64
	v_mov_b32_e32 v101, v64
	v_mov_b32_e32 v102, v64
	v_mov_b32_e32 v103, v64
	v_mov_b32_e32 v104, v64
	v_mov_b32_e32 v105, v64
	v_mov_b32_e32 v106, v64
	v_mov_b32_e32 v107, v64
	v_mov_b32_e32 v108, v64
	v_mov_b32_e32 v109, v64
	v_mov_b32_e32 v110, v64
	v_mov_b32_e32 v111, v64
	s_branch .LBB0_413

; #define LAS __attribute__((address_space(3)))
; template <int DV, int PAR, bool KW = true, bool KL = true, bool VL = true>
; __device__ __forceinline__ void attn_iter_full(AttnState<DV>& S, int t, LAS unsigned char* lds) {
;     ...
;     u32x4 pw[4]; float mxa = 0.f, mxb = 0.f, mx = 0.f; f32x16 ssum;
;     constexpr int PD = (DV == 64) ? 3 : 2; bf16x8 fr[PD + 1];
;     ...
; #pragma unroll
;     for (int i = 0; i < PD; ++i) fr[i] = AT_FRAG(i);
;     __builtin_amdgcn_sched_barrier(0);
; #pragma unroll
;     for (int i = 0; i < NS; ++i) {
;         if (i + PD < NS) fr[(i + PD) % (PD + 1)] = AT_FRAG(i + PD);
;         if (i == 3) {
;             if (KW) *(LAS u32x4*)(lds + AT_K0 + PAR * AT_KB + S.kl) = S.kreg;
;             LAS unsigned char* W = lds + AT_V0 + (PAR ^ 1) * AT_VB + S.vl; *(LAS u32x4*)W = S.vreg0; if (DV == 128) *(LAS u32x4*)(W + 64 * 144) = S.vreg1; }
;         if (i == 5) { if (KL) S.kreg = *(const u32x4*)(S.kg + (size_t)(t + 3) * 4096);
;             if (VL) { S.vreg0 = *(const u32x4*)(S.vg + (t + 2) * 64); if (DV == 128) S.vreg1 = *(const u32x4*)(S.vg + (size_t)64 * TK + (t + 2) * 64); } }
;         if (i < 8) { if (i & 1) sn1 = MFMA32(fr[i % (PD + 1)], S.qr[i >> 1], sn1); else sn0 = MFMA32(fr[i % (PD + 1)], S.qr[i >> 1], sn0); }
;         else { const int j = i - 8; S.o[j % NDB] = MFMA32(fr[i % (PD + 1)], __builtin_bit_cast(bf16x8, pw[j / NDB]), S.o[j % NDB]); }
; #pragma unroll
;         for (int u = 0; u < NU; ++u) {
;             if (u * NS / NU != i) continue;
;             if (u < 20) {
;                 const int q = u / 5, r = u % 5;
;                 if (r < 4) { const int e = 8 * q + 2 * r;
;                     if (e < 16) { C0[e] = fast_exp2(C0[e]); C0[e + 1] = fast_exp2(C0[e + 1]); }
;                     else { C1[e - 16] = fast_exp2(C1[e - 16]); C1[e - 15] = fast_exp2(C1[e - 15]); } }
;                 else { if (q < 2) { const int b0 = 8 * q; pw[q].x = pk2(C0[b0], C0[b0 + 1]); pw[q].y = pk2(C0[b0 + 2], C0[b0 + 3]); pw[q].z = pk2(C0[b0 + 4], C0[b0 + 5]); pw[q].w = pk2(C0[b0 + 6], C0[b0 + 7]); }
;                        else { const int b0 = 8 * (q - 2); pw[q].x = pk2(C1[b0], C1[b0 + 1]); pw[q].y = pk2(C1[b0 + 2], C1[b0 + 3]); pw[q].z = pk2(C1[b0 + 4], C1[b0 + 5]); pw[q].w = pk2(C1[b0 + 6], C1[b0 + 7]); } }
;             } else if (u == 20) { ssum = C0 + C1; }
.LBB0_427:
	ds_read_b128 v[64:67], v234 offset:9216
	ds_read_b128 v[68:71], v234 offset:13824
	s_waitcnt lgkmcnt(1)
	v_mfma_f32_32x32x16_bf16 v[144:159], v[64:67], v[174:177], v[96:111]
	ds_read_b128 v[72:75], v234 offset:9248
	v_exp_f32_e32 v64, v114
	v_exp_f32_e32 v66, v112
	v_exp_f32_e32 v67, v113
	v_exp_f32_e32 v65, v115
	s_waitcnt lgkmcnt(1)
	v_mfma_f32_32x32x16_bf16 v[128:143], v[68:71], v[174:177], v[96:111]
	ds_read_b128 v[76:79], v234 offset:13856
	v_exp_f32_e32 v68, v116
	v_exp_f32_e32 v69, v117
	s_waitcnt lgkmcnt(1)
	v_mfma_f32_32x32x16_bf16 v[144:159], v[72:75], v[170:173], v[144:159]
	ds_read_b128 v[112:115], v234 offset:9280
	v_lshl_add_u64 v[210:211], v[206:207], 0, v[160:161]
	v_lshl_add_u64 v[196:197], v[208:209], 0, v[160:161]
	v_exp_f32_e32 v70, v118
	v_exp_f32_e32 v71, v119
	s_waitcnt lgkmcnt(1)
	v_mfma_f32_32x32x16_bf16 v[128:143], v[76:79], v[170:173], v[128:143]
	ds_read_b128 v[116:119], v234 offset:13888
	s_waitcnt vmcnt(0)
	ds_write_b128 v235, v[186:189]
	ds_write_b128 v235, v[178:181] offset:36864
	ds_write_b128 v235, v[182:185] offset:46080
	v_cvt_pk_bf16_f32 v74, v66, v67
	v_cvt_pk_bf16_f32 v75, v64, v65
	v_cvt_pk_bf16_f32 v76, v68, v69
	v_cvt_pk_bf16_f32 v77, v70, v71
	s_waitcnt lgkmcnt(4)
	v_mfma_f32_32x32x16_bf16 v[144:159], v[112:115], v[166:169], v[144:159]
	ds_read_b128 v[190:193], v234 offset:9312
	v_exp_f32_e32 v72, v120
	v_exp_f32_e32 v73, v121
	s_mov_b32 s2, 0x10e8e000
	v_add_co_u32_e32 v78, vcc, s2, v210
	ds_read_b128 v[112:115], v234 offset:13920
	s_nop 0
	v_addc_co_u32_e32 v79, vcc, 0, v211, vcc
	v_add_co_u32_e32 v212, vcc, s4, v196
	global_load_dwordx4 v[178:181], v[78:79], off
	s_nop 0
	v_addc_co_u32_e32 v213, vcc, 0, v197, vcc
	v_add_co_u32_e32 v214, vcc, s5, v196
	global_load_dwordx4 v[182:185], v[212:213], off offset:256
	s_nop 0
	v_addc_co_u32_e32 v215, vcc, 0, v197, vcc
	global_load_dwordx4 v[186:189], v[214:215], off offset:256
	s_waitcnt lgkmcnt(5)
	v_mfma_f32_32x32x16_bf16 v[128:143], v[116:119], v[166:169], v[128:143]
	v_exp_f32_e32 v196, v122
	v_exp_f32_e32 v197, v123
	s_waitcnt lgkmcnt(1)
	v_mfma_f32_32x32x16_bf16 v[144:159], v[190:193], v[162:165], v[144:159]
	ds_read_b128 v[116:119], v233 offset:18432
	v_exp_f32_e32 v124, v124
	v_exp_f32_e32 v125, v125
	s_waitcnt lgkmcnt(1)
	v_mfma_f32_32x32x16_bf16 v[128:143], v[112:115], v[162:165], v[128:143]
	ds_read_b128 v[120:123], v233 offset:23040
	v_exp_f32_e32 v126, v126
	v_exp_f32_e32 v127, v127
	s_waitcnt lgkmcnt(1)
	v_mfma_f32_32x32x16_bf16 v[0:15], v[116:119], v[74:77], v[0:15]
	ds_read_b128 v[112:115], v233 offset:27648
	v_cvt_pk_bf16_f32 v116, v72, v73
	v_cvt_pk_bf16_f32 v117, v196, v197
	v_cvt_pk_bf16_f32 v118, v124, v125
	v_cvt_pk_bf16_f32 v119, v126, v127
	v_exp_f32_e32 v190, v80
	v_exp_f32_e32 v191, v81
	s_waitcnt lgkmcnt(1)
	v_mfma_f32_32x32x16_bf16 v[48:63], v[120:123], v[74:77], v[48:63]
	ds_read_b128 v[78:81], v233 offset:32256
	v_exp_f32_e32 v192, v82
	v_exp_f32_e32 v193, v83
	s_waitcnt lgkmcnt(1)
	v_mfma_f32_32x32x16_bf16 v[32:47], v[112:115], v[74:77], v[32:47]
	ds_read_b128 v[120:123], v233 offset:18464
	v_exp_f32_e32 v198, v84
	v_exp_f32_e32 v199, v85
	s_waitcnt lgkmcnt(1)
	v_mfma_f32_32x32x16_bf16 v[16:31], v[78:81], v[74:77], v[16:31]
	ds_read_b128 v[82:85], v233 offset:23072
	v_exp_f32_e32 v242, v86
	v_exp_f32_e32 v243, v87
	s_waitcnt lgkmcnt(1)
	v_mfma_f32_32x32x16_bf16 v[0:15], v[120:123], v[116:119], v[0:15]
	ds_read_b128 v[74:77], v233 offset:27680
	v_cvt_pk_bf16_f32 v78, v190, v191
	v_cvt_pk_bf16_f32 v79, v192, v193
	v_cvt_pk_bf16_f32 v80, v198, v199
	v_cvt_pk_bf16_f32 v81, v242, v243
	s_waitcnt lgkmcnt(1)
	v_mfma_f32_32x32x16_bf16 v[48:63], v[82:85], v[116:119], v[48:63]
	ds_read_b128 v[112:115], v233 offset:32288
	v_exp_f32_e32 v120, v88
	v_exp_f32_e32 v121, v89
	s_waitcnt lgkmcnt(1)
	v_mfma_f32_32x32x16_bf16 v[32:47], v[74:77], v[116:119], v[32:47]
	ds_read_b128 v[82:85], v233 offset:18496
	v_exp_f32_e32 v122, v90
	v_exp_f32_e32 v123, v91
	s_waitcnt lgkmcnt(1)
	v_mfma_f32_32x32x16_bf16 v[16:31], v[112:115], v[116:119], v[16:31]
	ds_read_b128 v[74:77], v233 offset:23104
	v_exp_f32_e32 v112, v92
	v_exp_f32_e32 v113, v93
	s_waitcnt lgkmcnt(1)
	v_mfma_f32_32x32x16_bf16 v[0:15], v[82:85], v[78:81], v[0:15]
	ds_read_b128 v[86:89], v233 offset:27712
	v_exp_f32_e32 v94, v94
	v_exp_f32_e32 v95, v95
	v_cvt_pk_bf16_f32 v82, v120, v121
	v_cvt_pk_bf16_f32 v83, v122, v123
	v_cvt_pk_bf16_f32 v84, v112, v113
	v_cvt_pk_bf16_f32 v85, v94, v95
	s_waitcnt lgkmcnt(1)
	v_mfma_f32_32x32x16_bf16 v[48:63], v[74:77], v[78:81], v[48:63]
	ds_read_b128 v[90:93], v233 offset:32320
	v_add_f32_e64 v74, v124, v112
	v_add_f32_e64 v75, v125, v113
	v_add_f32_e64 v76, v126, v94
	v_add_f32_e64 v77, v127, v95
	v_pk_add_f32 v[94:95], v[196:197], v[122:123]
	v_pk_add_f32 v[72:73], v[72:73], v[120:121]
	v_pk_add_f32 v[68:69], v[68:69], v[198:199]
	v_pk_add_f32 v[112:113], v[66:67], v[190:191]
	v_pk_add_f32 v[70:71], v[70:71], v[242:243]
	v_pk_add_f32 v[114:115], v[64:65], v[192:193]
	s_waitcnt lgkmcnt(1)
	v_mfma_f32_32x32x16_bf16 v[32:47], v[86:89], v[78:81], v[32:47]
	v_add_f32_e64 v70, v114, v70
	v_add_f32_e64 v71, v115, v71
	v_add_f32_e64 v68, v112, v68
	v_add_f32_e64 v69, v113, v69
	v_add_f32_e64 v70, v94, v70
	v_add_f32_e64 v71, v95, v71
	v_pk_add_f32 v[68:69], v[72:73], v[68:69]
	ds_read_b128 v[64:67], v233 offset:18528
	v_pk_add_f32 v[70:71], v[76:77], v[70:71]
	v_pk_add_f32 v[68:69], v[74:75], v[68:69]
	s_nop 0
	v_pk_mov_b32 v[72:73], v[68:69], v[70:71] op_sel:[1,0]
	v_mov_b32_e32 v69, v71
	v_pk_add_f32 v[68:69], v[72:73], v[68:69]
	s_nop 0
	v_add_f32_e32 v68, v68, v69
	v_add_f32_e32 v237, v216, v68
	s_waitcnt lgkmcnt(1)
	v_mfma_f32_32x32x16_bf16 v[16:31], v[90:93], v[78:81], v[16:31]
	ds_read_b128 v[68:71], v233 offset:23136
	v_max3_f32 v72, v144, v145, v128
	v_max3_f32 v76, v146, v147, v129
	v_max3_f32 v77, v72, v130, v131
	s_waitcnt lgkmcnt(1)
	v_mfma_f32_32x32x16_bf16 v[0:15], v[64:67], v[82:85], v[0:15]
	ds_read_b128 v[72:75], v233 offset:27744
	v_max3_f32 v64, v77, v148, v149
	v_max3_f32 v65, v76, v150, v151
	v_max3_f32 v76, v64, v132, v133
	v_max3_f32 v77, v65, v134, v135
	s_waitcnt lgkmcnt(1)
	v_mfma_f32_32x32x16_bf16 v[48:63], v[68:71], v[82:85], v[48:63]
	ds_read_b128 v[64:67], v233 offset:32352
	v_max3_f32 v68, v76, v152, v153
	v_max3_f32 v69, v77, v154, v155
	v_max3_f32 v68, v68, v136, v137
	v_max3_f32 v69, v69, v138, v139
	s_waitcnt lgkmcnt(1)
	v_mfma_f32_32x32x16_bf16 v[32:47], v[72:75], v[82:85], v[32:47]
	v_max3_f32 v68, v68, v156, v157
	v_max3_f32 v69, v69, v158, v159
	v_max3_f32 v68, v68, v140, v141
	v_max3_f32 v69, v69, v142, v143
	s_waitcnt lgkmcnt(0)
	v_mfma_f32_32x32x16_bf16 v[16:31], v[64:67], v[82:85], v[16:31]
	v_max_f32_e32 v64, v68, v69
	v_mov_b32_e32 v65, v64
	s_nop 1
	v_permlane32_swap_b32_e32 v64, v65
	v_max_f32_e32 v64, v64, v65
	s_nop 0
	v_cmp_lt_f32_e32 vcc, s3, v64
	s_cbranch_vccz .LBB0_429
; __device__ __forceinline__ float fast_exp2(float x) { return __builtin_amdgcn_exp2f(x); }
; template <int DV, int PAR, bool KW = true, bool KL = true, bool VL = true>
; __device__ __forceinline__ void attn_iter_full(AttnState<DV>& S, int t, LAS unsigned char* lds) {
;     ...
;     if (__any(mx > 8.0f)) {
;         const float dl = fmaxf(mx, 0.f), alpha = fast_exp2(-dl);
;         S.mrun += dl; S.lsum *= alpha;
; #pragma unroll
;         for (int i = 0; i < 16; ++i) { sn0[i] -= dl; sn1[i] -= dl; S.negm[i] = -S.mrun; }
; #pragma unroll
;         for (int d = 0; d < NDB; ++d)
; #pragma unroll
;             for (int i = 0; i < 16; ++i) S.o[d][i] *= alpha;
;     }
	v_max_f32_e32 v64, v64, v64
	v_max_f32_e32 v66, 0, v64
	v_exp_f32_e64 v68, -v66
	v_add_f32_e32 v236, v236, v66
	v_xor_b32_e32 v64, 0x80000000, v236
	v_pk_add_f32 v[144:145], v[144:145], v[66:67] op_sel_hi:[1,0] neg_lo:[0,1] neg_hi:[0,1]
	v_mul_f32_e32 v237, v237, v68
	v_pk_add_f32 v[128:129], v[128:129], v[66:67] op_sel_hi:[1,0] neg_lo:[0,1] neg_hi:[0,1]
	v_pk_add_f32 v[146:147], v[146:147], v[66:67] op_sel_hi:[1,0] neg_lo:[0,1] neg_hi:[0,1]
	v_pk_add_f32 v[130:131], v[130:131], v[66:67] op_sel_hi:[1,0] neg_lo:[0,1] neg_hi:[0,1]
	v_pk_add_f32 v[148:149], v[148:149], v[66:67] op_sel_hi:[1,0] neg_lo:[0,1] neg_hi:[0,1]
	v_pk_add_f32 v[132:133], v[132:133], v[66:67] op_sel_hi:[1,0] neg_lo:[0,1] neg_hi:[0,1]
	v_pk_add_f32 v[150:151], v[150:151], v[66:67] op_sel_hi:[1,0] neg_lo:[0,1] neg_hi:[0,1]
	v_pk_add_f32 v[134:135], v[134:135], v[66:67] op_sel_hi:[1,0] neg_lo:[0,1] neg_hi:[0,1]
	v_pk_add_f32 v[152:153], v[152:153], v[66:67] op_sel_hi:[1,0] neg_lo:[0,1] neg_hi:[0,1]
	v_pk_add_f32 v[136:137], v[136:137], v[66:67] op_sel_hi:[1,0] neg_lo:[0,1] neg_hi:[0,1]
	v_pk_add_f32 v[154:155], v[154:155], v[66:67] op_sel_hi:[1,0] neg_lo:[0,1] neg_hi:[0,1]
	v_pk_add_f32 v[138:139], v[138:139], v[66:67] op_sel_hi:[1,0] neg_lo:[0,1] neg_hi:[0,1]
	v_pk_add_f32 v[156:157], v[156:157], v[66:67] op_sel_hi:[1,0] neg_lo:[0,1] neg_hi:[0,1]
	v_pk_add_f32 v[140:141], v[140:141], v[66:67] op_sel_hi:[1,0] neg_lo:[0,1] neg_hi:[0,1]
	v_pk_add_f32 v[158:159], v[158:159], v[66:67] op_sel_hi:[1,0] neg_lo:[0,1] neg_hi:[0,1]
	v_pk_add_f32 v[142:143], v[142:143], v[66:67] op_sel_hi:[1,0] neg_lo:[0,1] neg_hi:[0,1]
	v_pk_mul_f32 v[14:15], v[14:15], v[68:69] op_sel_hi:[1,0]
	v_pk_mul_f32 v[12:13], v[12:13], v[68:69] op_sel_hi:[1,0]
	v_pk_mul_f32 v[10:11], v[10:11], v[68:69] op_sel_hi:[1,0]
	v_pk_mul_f32 v[8:9], v[8:9], v[68:69] op_sel_hi:[1,0]
	v_pk_mul_f32 v[6:7], v[6:7], v[68:69] op_sel_hi:[1,0]
	v_pk_mul_f32 v[4:5], v[4:5], v[68:69] op_sel_hi:[1,0]
	v_pk_mul_f32 v[2:3], v[2:3], v[68:69] op_sel_hi:[1,0]
	v_pk_mul_f32 v[0:1], v[0:1], v[68:69] op_sel_hi:[1,0]
	v_pk_mul_f32 v[62:63], v[62:63], v[68:69] op_sel_hi:[1,0]
	v_pk_mul_f32 v[60:61], v[60:61], v[68:69] op_sel_hi:[1,0]
	v_pk_mul_f32 v[58:59], v[58:59], v[68:69] op_sel_hi:[1,0]
	v_pk_mul_f32 v[56:57], v[56:57], v[68:69] op_sel_hi:[1,0]
	v_pk_mul_f32 v[54:55], v[54:55], v[68:69] op_sel_hi:[1,0]
	v_pk_mul_f32 v[52:53], v[52:53], v[68:69] op_sel_hi:[1,0]
	v_pk_mul_f32 v[50:51], v[50:51], v[68:69] op_sel_hi:[1,0]
	v_pk_mul_f32 v[48:49], v[48:49], v[68:69] op_sel_hi:[1,0]
	v_pk_mul_f32 v[46:47], v[46:47], v[68:69] op_sel_hi:[1,0]
	v_pk_mul_f32 v[44:45], v[44:45], v[68:69] op_sel_hi:[1,0]
	v_pk_mul_f32 v[42:43], v[42:43], v[68:69] op_sel_hi:[1,0]
	v_pk_mul_f32 v[40:41], v[40:41], v[68:69] op_sel_hi:[1,0]
	v_pk_mul_f32 v[38:39], v[38:39], v[68:69] op_sel_hi:[1,0]
	v_pk_mul_f32 v[36:37], v[36:37], v[68:69] op_sel_hi:[1,0]
	v_pk_mul_f32 v[34:35], v[34:35], v[68:69] op_sel_hi:[1,0]
	v_pk_mul_f32 v[32:33], v[32:33], v[68:69] op_sel_hi:[1,0]
	v_pk_mul_f32 v[30:31], v[30:31], v[68:69] op_sel_hi:[1,0]
	v_pk_mul_f32 v[28:29], v[28:29], v[68:69] op_sel_hi:[1,0]
	v_pk_mul_f32 v[26:27], v[26:27], v[68:69] op_sel_hi:[1,0]
	v_pk_mul_f32 v[24:25], v[24:25], v[68:69] op_sel_hi:[1,0]
	v_pk_mul_f32 v[22:23], v[22:23], v[68:69] op_sel_hi:[1,0]
	v_pk_mul_f32 v[20:21], v[20:21], v[68:69] op_sel_hi:[1,0]
	v_pk_mul_f32 v[18:19], v[18:19], v[68:69] op_sel_hi:[1,0]
	v_pk_mul_f32 v[16:17], v[16:17], v[68:69] op_sel_hi:[1,0]
	v_mov_b32_e32 v65, v64
	v_mov_b32_e32 v66, v64
	v_mov_b32_e32 v67, v64
	v_mov_b32_e32 v68, v64
	v_mov_b32_e32 v69, v64
	v_mov_b32_e32 v70, v64
	v_mov_b32_e32 v71, v64
	v_mov_b32_e32 v72, v64
	v_mov_b32_e32 v73, v64
	v_mov_b32_e32 v74, v64
	v_mov_b32_e32 v75, v64
	v_mov_b32_e32 v76, v64
	v_mov_b32_e32 v77, v64
	v_mov_b32_e32 v78, v64
	v_mov_b32_e32 v79, v64
	v_mov_b32_e32 v96, v64
	v_mov_b32_e32 v97, v64
	v_mov_b32_e32 v98, v64
	v_mov_b32_e32 v99, v64
	v_mov_b32_e32 v100, v64
	v_mov_b32_e32 v101, v64
	v_mov_b32_e32 v102, v64
	v_mov_b32_e32 v103, v64
	v_mov_b32_e32 v104, v64
	v_mov_b32_e32 v105, v64
	v_mov_b32_e32 v106, v64
	v_mov_b32_e32 v107, v64
	v_mov_b32_e32 v108, v64
	v_mov_b32_e32 v109, v64
	v_mov_b32_e32 v110, v64
	v_mov_b32_e32 v111, v64
	s_branch .LBB0_430
; #define LAS __attribute__((address_space(3)))
; template <int DV, int PAR, bool KW = true, bool KL = true, bool VL = true>
; __device__ __forceinline__ void attn_iter_full(AttnState<DV>& S, int t, LAS unsigned char* lds) {
;     ...
;     u32x4 pw[4]; float mxa = 0.f, mxb = 0.f, mx = 0.f; f32x16 ssum;
;     constexpr int PD = (DV == 64) ? 3 : 2; bf16x8 fr[PD + 1];
;     ...
; #pragma unroll
;     for (int i = 0; i < PD; ++i) fr[i] = AT_FRAG(i);
;     __builtin_amdgcn_sched_barrier(0);
; #pragma unroll
;     for (int i = 0; i < NS; ++i) {
;         if (i + PD < NS) fr[(i + PD) % (PD + 1)] = AT_FRAG(i + PD);
;         if (i == 3) {
;             if (KW) *(LAS u32x4*)(lds + AT_K0 + PAR * AT_KB + S.kl) = S.kreg;
;             LAS unsigned char* W = lds + AT_V0 + (PAR ^ 1) * AT_VB + S.vl; *(LAS u32x4*)W = S.vreg0; if (DV == 128) *(LAS u32x4*)(W + 64 * 144) = S.vreg1; }
;         if (i == 5) { if (KL) S.kreg = *(const u32x4*)(S.kg + (size_t)(t + 3) * 4096);
;             if (VL) { S.vreg0 = *(const u32x4*)(S.vg + (t + 2) * 64); if (DV == 128) S.vreg1 = *(const u32x4*)(S.vg + (size_t)64 * TK + (t + 2) * 64); } }
;         if (i < 8) { if (i & 1) sn1 = MFMA32(fr[i % (PD + 1)], S.qr[i >> 1], sn1); else sn0 = MFMA32(fr[i % (PD + 1)], S.qr[i >> 1], sn0); }
;         else { const int j = i - 8; S.o[j % NDB] = MFMA32(fr[i % (PD + 1)], __builtin_bit_cast(bf16x8, pw[j / NDB]), S.o[j % NDB]); }
; #pragma unroll
;         for (int u = 0; u < NU; ++u) {
;             if (u * NS / NU != i) continue;
;             if (u < 20) {
;                 const int q = u / 5, r = u % 5;
;                 if (r < 4) { const int e = 8 * q + 2 * r;
;                     if (e < 16) { C0[e] = fast_exp2(C0[e]); C0[e + 1] = fast_exp2(C0[e + 1]); }
;                     else { C1[e - 16] = fast_exp2(C1[e - 16]); C1[e - 15] = fast_exp2(C1[e - 15]); } }
;                 else { if (q < 2) { const int b0 = 8 * q; pw[q].x = pk2(C0[b0], C0[b0 + 1]); pw[q].y = pk2(C0[b0 + 2], C0[b0 + 3]); pw[q].z = pk2(C0[b0 + 4], C0[b0 + 5]); pw[q].w = pk2(C0[b0 + 6], C0[b0 + 7]); }
;                        else { const int b0 = 8 * (q - 2); pw[q].x = pk2(C1[b0], C1[b0 + 1]); pw[q].y = pk2(C1[b0 + 2], C1[b0 + 3]); pw[q].z = pk2(C1[b0 + 4], C1[b0 + 5]); pw[q].w = pk2(C1[b0 + 6], C1[b0 + 7]); } }
;             } else if (u == 20) { ssum = C0 + C1; }
.LBB0_429:
.LBB0_430:
	s_barrier
	ds_read_b128 v[80:83], v234
	ds_read_b128 v[190:193], v234 offset:4608
	s_waitcnt lgkmcnt(1)
	v_mfma_f32_32x32x16_bf16 v[112:127], v[80:83], v[174:177], v[96:111]
	ds_read_b128 v[196:199], v234 offset:32
	v_exp_f32_e32 v216, v144
	v_exp_f32_e32 v217, v145
	v_exp_f32_e32 v144, v146
	v_exp_f32_e32 v145, v147
	s_waitcnt lgkmcnt(1)
	v_mfma_f32_32x32x16_bf16 v[80:95], v[190:193], v[174:177], v[96:111]
	ds_read_b128 v[242:245], v234 offset:4640
	v_exp_f32_e32 v146, v148
	v_exp_f32_e32 v147, v149
	s_waitcnt lgkmcnt(1)
	v_mfma_f32_32x32x16_bf16 v[112:127], v[196:199], v[170:173], v[112:127]
	ds_read_b128 v[190:193], v234 offset:64
	v_exp_f32_e32 v148, v150
	v_exp_f32_e32 v149, v151
	s_waitcnt lgkmcnt(1)
	v_mfma_f32_32x32x16_bf16 v[80:95], v[242:245], v[170:173], v[80:95]
	ds_read_b128 v[196:199], v234 offset:4672
	s_waitcnt vmcnt(2)
	ds_write_b128 v235, v[178:181] offset:9216
	s_waitcnt vmcnt(1)
	ds_write_b128 v235, v[182:185] offset:18432
	s_waitcnt vmcnt(0)
	ds_write_b128 v235, v[186:189] offset:27648
	v_cvt_pk_bf16_f32 v246, v216, v217
	v_cvt_pk_bf16_f32 v247, v144, v145
	v_cvt_pk_bf16_f32 v248, v146, v147
	v_cvt_pk_bf16_f32 v249, v148, v149
	s_waitcnt lgkmcnt(4)
	v_mfma_f32_32x32x16_bf16 v[112:127], v[190:193], v[166:169], v[112:127]
	ds_read_b128 v[242:245], v234 offset:96
	v_exp_f32_e32 v150, v152
	v_exp_f32_e32 v151, v153
	s_mov_b32 s2, 0x10e90000
	v_add_co_u32_e32 v152, vcc, s2, v210
	ds_read_b128 v[190:193], v234 offset:4704
	s_nop 0
	v_addc_co_u32_e32 v153, vcc, 0, v211, vcc
	global_load_dwordx4 v[186:189], v[152:153], off
	global_load_dwordx4 v[178:181], v[212:213], off offset:384
	global_load_dwordx4 v[182:185], v[214:215], off offset:384
	s_waitcnt lgkmcnt(5)
	v_mfma_f32_32x32x16_bf16 v[80:95], v[196:199], v[166:169], v[80:95]
	v_exp_f32_e32 v210, v154
	v_exp_f32_e32 v211, v155
	s_waitcnt lgkmcnt(1)
	v_mfma_f32_32x32x16_bf16 v[112:127], v[242:245], v[162:165], v[112:127]
	ds_read_b128 v[152:155], v233 offset:36864
	v_exp_f32_e32 v212, v156
	v_exp_f32_e32 v213, v157
	s_waitcnt lgkmcnt(1)
	v_mfma_f32_32x32x16_bf16 v[80:95], v[190:193], v[162:165], v[80:95]
	ds_read_b128 v[196:199], v233 offset:41472
	v_exp_f32_e32 v214, v158
	v_exp_f32_e32 v215, v159
	s_waitcnt lgkmcnt(1)
	v_mfma_f32_32x32x16_bf16 v[0:15], v[152:155], v[246:249], v[0:15]
	ds_read_b128 v[156:159], v233 offset:46080
	v_cvt_pk_bf16_f32 v152, v150, v151
	v_cvt_pk_bf16_f32 v153, v210, v211
	v_cvt_pk_bf16_f32 v154, v212, v213
	v_cvt_pk_bf16_f32 v155, v214, v215
	v_exp_f32_e32 v242, v128
	v_exp_f32_e32 v243, v129
	s_waitcnt lgkmcnt(1)
	v_mfma_f32_32x32x16_bf16 v[48:63], v[196:199], v[246:249], v[48:63]
	ds_read_b128 v[190:193], v233 offset:50688
	v_exp_f32_e32 v196, v130
	v_exp_f32_e32 v197, v131
	s_waitcnt lgkmcnt(1)
	v_mfma_f32_32x32x16_bf16 v[32:47], v[156:159], v[246:249], v[32:47]
	ds_read_b128 v[128:131], v233 offset:36896
	v_exp_f32_e32 v198, v132
	v_exp_f32_e32 v199, v133
	s_waitcnt lgkmcnt(1)
	v_mfma_f32_32x32x16_bf16 v[16:31], v[190:193], v[246:249], v[16:31]
	ds_read_b128 v[156:159], v233 offset:41504
	v_exp_f32_e32 v244, v134
	v_exp_f32_e32 v245, v135
	s_waitcnt lgkmcnt(1)
	v_mfma_f32_32x32x16_bf16 v[0:15], v[128:131], v[152:155], v[0:15]
	ds_read_b128 v[132:135], v233 offset:46112
	v_cvt_pk_bf16_f32 v128, v242, v243
	v_cvt_pk_bf16_f32 v129, v196, v197
	v_cvt_pk_bf16_f32 v130, v198, v199
	v_cvt_pk_bf16_f32 v131, v244, v245
	s_waitcnt lgkmcnt(1)
	v_mfma_f32_32x32x16_bf16 v[48:63], v[156:159], v[152:155], v[48:63]
	ds_read_b128 v[190:193], v233 offset:50720
	v_exp_f32_e32 v246, v136
	v_exp_f32_e32 v247, v137
	s_waitcnt lgkmcnt(1)
	v_mfma_f32_32x32x16_bf16 v[32:47], v[132:135], v[152:155], v[32:47]
	ds_read_b128 v[156:159], v233 offset:36928
	v_exp_f32_e32 v248, v138
	v_exp_f32_e32 v249, v139
	s_waitcnt lgkmcnt(1)
	v_mfma_f32_32x32x16_bf16 v[16:31], v[190:193], v[152:155], v[16:31]
	ds_read_b128 v[132:135], v233 offset:41536
	v_exp_f32_e32 v190, v140
	v_exp_f32_e32 v191, v141
	s_waitcnt lgkmcnt(1)
	v_mfma_f32_32x32x16_bf16 v[0:15], v[156:159], v[128:131], v[0:15]
	ds_read_b128 v[136:139], v233 offset:46144
	v_exp_f32_e32 v156, v142
	v_exp_f32_e32 v157, v143
	v_cvt_pk_bf16_f32 v140, v246, v247
	v_cvt_pk_bf16_f32 v141, v248, v249
	v_cvt_pk_bf16_f32 v142, v190, v191
	v_cvt_pk_bf16_f32 v143, v156, v157
	s_waitcnt lgkmcnt(1)
	v_mfma_f32_32x32x16_bf16 v[48:63], v[132:135], v[128:131], v[48:63]
	ds_read_b128 v[152:155], v233 offset:50752
	v_add_f32_e64 v158, v212, v190
	v_add_f32_e64 v159, v213, v191
	v_add_f32_e64 v156, v214, v156
	v_add_f32_e64 v157, v215, v157
	v_pk_add_f32 v[190:191], v[210:211], v[248:249]
	v_pk_add_f32 v[150:151], v[150:151], v[246:247]
	v_pk_add_f32 v[146:147], v[146:147], v[198:199]
	v_pk_add_f32 v[192:193], v[216:217], v[242:243]
	v_pk_add_f32 v[148:149], v[148:149], v[244:245]
	v_pk_add_f32 v[144:145], v[144:145], v[196:197]
	s_waitcnt lgkmcnt(1)
	v_mfma_f32_32x32x16_bf16 v[32:47], v[136:139], v[128:131], v[32:47]
	v_add_f32_e64 v136, v144, v148
	v_add_f32_e64 v137, v145, v149
	v_add_f32_e64 v138, v192, v146
	v_add_f32_e64 v139, v193, v147
	v_add_f32_e64 v136, v190, v136
	v_add_f32_e64 v137, v191, v137
	v_pk_add_f32 v[138:139], v[150:151], v[138:139]
	v_pk_add_f32 v[136:137], v[156:157], v[136:137]
	v_pk_add_f32 v[138:139], v[158:159], v[138:139]
	ds_read_b128 v[132:135], v233 offset:36960
	v_pk_mov_b32 v[144:145], v[138:139], v[136:137] op_sel:[1,0]
	v_mov_b32_e32 v139, v137
	v_pk_add_f32 v[136:137], v[144:145], v[138:139]
	s_nop 0
	v_add_f32_e32 v136, v136, v137
	v_add_f32_e32 v216, v237, v136
	s_waitcnt lgkmcnt(1)
	v_mfma_f32_32x32x16_bf16 v[16:31], v[152:155], v[128:131], v[16:31]
	ds_read_b128 v[136:139], v233 offset:41568
	v_max3_f32 v128, v112, v113, v80
	v_max3_f32 v144, v114, v115, v81
	v_max3_f32 v145, v128, v82, v83
	s_waitcnt lgkmcnt(1)
	v_mfma_f32_32x32x16_bf16 v[0:15], v[132:135], v[140:143], v[0:15]
	ds_read_b128 v[128:131], v233 offset:46176
	v_max3_f32 v132, v145, v116, v117
	v_max3_f32 v133, v144, v118, v119
	v_max3_f32 v144, v132, v84, v85
	v_max3_f32 v145, v133, v86, v87
	s_waitcnt lgkmcnt(1)
	v_mfma_f32_32x32x16_bf16 v[48:63], v[136:139], v[140:143], v[48:63]
	ds_read_b128 v[132:135], v233 offset:50784
	v_max3_f32 v136, v144, v120, v121
	v_max3_f32 v137, v145, v122, v123
	v_max3_f32 v136, v136, v88, v89
	v_max3_f32 v137, v137, v90, v91
	s_waitcnt lgkmcnt(1)
	v_mfma_f32_32x32x16_bf16 v[32:47], v[128:131], v[140:143], v[32:47]
	v_max3_f32 v128, v136, v124, v125
	v_max3_f32 v129, v137, v126, v127
	v_max3_f32 v128, v128, v92, v93
	v_max3_f32 v129, v129, v94, v95
	s_waitcnt lgkmcnt(0)
	v_mfma_f32_32x32x16_bf16 v[16:31], v[132:135], v[140:143], v[16:31]
	v_max_f32_e32 v128, v128, v129
	v_mov_b32_e32 v129, v128
	s_nop 1
	v_permlane32_swap_b32_e32 v128, v129
	v_max_f32_e32 v128, v128, v129
	s_nop 0
	v_cmp_lt_f32_e32 vcc, s3, v128
	s_cbranch_vccz .LBB0_426
; __device__ __forceinline__ float fast_exp2(float x) { return __builtin_amdgcn_exp2f(x); }
; template <int DV, int PAR, bool KW = true, bool KL = true, bool VL = true>
; __device__ __forceinline__ void attn_iter_full(AttnState<DV>& S, int t, LAS unsigned char* lds) {
;     ...
;     if (__any(mx > 8.0f)) {
;         const float dl = fmaxf(mx, 0.f), alpha = fast_exp2(-dl);
;         S.mrun += dl; S.lsum *= alpha;
; #pragma unroll
;         for (int i = 0; i < 16; ++i) { sn0[i] -= dl; sn1[i] -= dl; S.negm[i] = -S.mrun; }
; #pragma unroll
;         for (int d = 0; d < NDB; ++d)
; #pragma unroll
;             for (int i = 0; i < 16; ++i) S.o[d][i] *= alpha;
;     }
	v_max_f32_e32 v64, v128, v128
	v_max_f32_e32 v65, 0, v64
	v_exp_f32_e64 v66, -v65
	v_add_f32_e32 v236, v236, v65
	v_xor_b32_e32 v64, 0x80000000, v236
	v_sub_f32_e32 v127, v127, v65
	v_mul_f32_e32 v216, v216, v66
	v_sub_f32_e32 v126, v126, v65
	v_sub_f32_e32 v125, v125, v65
	v_sub_f32_e32 v124, v124, v65
	v_sub_f32_e32 v123, v123, v65
	v_sub_f32_e32 v122, v122, v65
	v_sub_f32_e32 v121, v121, v65
	v_sub_f32_e32 v120, v120, v65
	v_sub_f32_e32 v119, v119, v65
	v_sub_f32_e32 v118, v118, v65
	v_sub_f32_e32 v117, v117, v65
	v_sub_f32_e32 v116, v116, v65
	v_sub_f32_e32 v115, v115, v65
	v_sub_f32_e32 v114, v114, v65
	v_sub_f32_e32 v113, v113, v65
	v_sub_f32_e32 v112, v112, v65
	v_sub_f32_e32 v95, v95, v65
	v_sub_f32_e32 v94, v94, v65
	v_sub_f32_e32 v93, v93, v65
	v_sub_f32_e32 v92, v92, v65
	v_sub_f32_e32 v91, v91, v65
	v_sub_f32_e32 v90, v90, v65
	v_sub_f32_e32 v89, v89, v65
	v_sub_f32_e32 v88, v88, v65
	v_sub_f32_e32 v87, v87, v65
	v_sub_f32_e32 v86, v86, v65
	v_sub_f32_e32 v85, v85, v65
	v_sub_f32_e32 v84, v84, v65
	v_sub_f32_e32 v83, v83, v65
	v_sub_f32_e32 v82, v82, v65
	v_sub_f32_e32 v81, v81, v65
	v_sub_f32_e32 v80, v80, v65
	v_pk_mul_f32 v[14:15], v[14:15], v[66:67] op_sel_hi:[1,0]
	v_pk_mul_f32 v[12:13], v[12:13], v[66:67] op_sel_hi:[1,0]
	v_pk_mul_f32 v[10:11], v[10:11], v[66:67] op_sel_hi:[1,0]
	v_pk_mul_f32 v[8:9], v[8:9], v[66:67] op_sel_hi:[1,0]
	v_pk_mul_f32 v[6:7], v[6:7], v[66:67] op_sel_hi:[1,0]
	v_pk_mul_f32 v[4:5], v[4:5], v[66:67] op_sel_hi:[1,0]
	v_pk_mul_f32 v[2:3], v[2:3], v[66:67] op_sel_hi:[1,0]
	v_pk_mul_f32 v[0:1], v[0:1], v[66:67] op_sel_hi:[1,0]
	v_pk_mul_f32 v[62:63], v[62:63], v[66:67] op_sel_hi:[1,0]
	v_pk_mul_f32 v[60:61], v[60:61], v[66:67] op_sel_hi:[1,0]
	v_pk_mul_f32 v[58:59], v[58:59], v[66:67] op_sel_hi:[1,0]
	v_pk_mul_f32 v[56:57], v[56:57], v[66:67] op_sel_hi:[1,0]
	v_pk_mul_f32 v[54:55], v[54:55], v[66:67] op_sel_hi:[1,0]
	v_pk_mul_f32 v[52:53], v[52:53], v[66:67] op_sel_hi:[1,0]
	v_pk_mul_f32 v[50:51], v[50:51], v[66:67] op_sel_hi:[1,0]
	v_pk_mul_f32 v[48:49], v[48:49], v[66:67] op_sel_hi:[1,0]
	v_pk_mul_f32 v[46:47], v[46:47], v[66:67] op_sel_hi:[1,0]
	v_pk_mul_f32 v[44:45], v[44:45], v[66:67] op_sel_hi:[1,0]
	v_pk_mul_f32 v[42:43], v[42:43], v[66:67] op_sel_hi:[1,0]
	v_pk_mul_f32 v[40:41], v[40:41], v[66:67] op_sel_hi:[1,0]
	v_pk_mul_f32 v[38:39], v[38:39], v[66:67] op_sel_hi:[1,0]
	v_pk_mul_f32 v[36:37], v[36:37], v[66:67] op_sel_hi:[1,0]
	v_pk_mul_f32 v[34:35], v[34:35], v[66:67] op_sel_hi:[1,0]
	v_pk_mul_f32 v[32:33], v[32:33], v[66:67] op_sel_hi:[1,0]
	v_pk_mul_f32 v[30:31], v[30:31], v[66:67] op_sel_hi:[1,0]
	v_pk_mul_f32 v[28:29], v[28:29], v[66:67] op_sel_hi:[1,0]
	v_pk_mul_f32 v[26:27], v[26:27], v[66:67] op_sel_hi:[1,0]
	v_pk_mul_f32 v[24:25], v[24:25], v[66:67] op_sel_hi:[1,0]
	v_pk_mul_f32 v[22:23], v[22:23], v[66:67] op_sel_hi:[1,0]
	v_pk_mul_f32 v[20:21], v[20:21], v[66:67] op_sel_hi:[1,0]
	v_pk_mul_f32 v[18:19], v[18:19], v[66:67] op_sel_hi:[1,0]
	v_pk_mul_f32 v[16:17], v[16:17], v[66:67] op_sel_hi:[1,0]
	v_mov_b32_e32 v65, v64
	v_mov_b32_e32 v66, v64
	v_mov_b32_e32 v67, v64
	v_mov_b32_e32 v68, v64
	v_mov_b32_e32 v69, v64
	v_mov_b32_e32 v70, v64
	v_mov_b32_e32 v71, v64
	v_mov_b32_e32 v72, v64
	v_mov_b32_e32 v73, v64
	v_mov_b32_e32 v74, v64
	v_mov_b32_e32 v75, v64
	v_mov_b32_e32 v76, v64
	v_mov_b32_e32 v77, v64
	v_mov_b32_e32 v78, v64
	v_mov_b32_e32 v79, v64
	v_mov_b32_e32 v96, v64
	v_mov_b32_e32 v97, v64
	v_mov_b32_e32 v98, v64
	v_mov_b32_e32 v99, v64
	v_mov_b32_e32 v100, v64
	v_mov_b32_e32 v101, v64
	v_mov_b32_e32 v102, v64
	v_mov_b32_e32 v103, v64
	v_mov_b32_e32 v104, v64
	v_mov_b32_e32 v105, v64
	v_mov_b32_e32 v106, v64
	v_mov_b32_e32 v107, v64
	v_mov_b32_e32 v108, v64
	v_mov_b32_e32 v109, v64
	v_mov_b32_e32 v110, v64
	v_mov_b32_e32 v111, v64
	s_branch .LBB0_426
